# 32 wave_sum butterfly reductions now DPP/permlane (adds D==T variant of the chain)
# speedup vs baseline: 1.0004x; 1.0004x over previous
; __device__ __forceinline__ float wave_sum(float v) {
; #pragma unroll
;     for (int o = 1; o < 64; o <<= 1) v += __shfl_xor(v, o);
;     return v;
; __device__ __forceinline__ void postnorm(const Ctx& c, const bf16* MF, bf16* XB, float* RS, const float* gpost, float* OUT) {
;     ...
;         const v4u* mr = (const v4u*)(MF + (size_t)row * DM) + c.lane; v4u* xr = (v4u*)(XB + (size_t)row * DM) + c.lane;
;         v4u mv[4], xv[4]; float v[4][8]; float s = 0.f;
; #pragma unroll
;         for (int j = 0; j < 4; ++j) { mv[j] = mr[64 * j]; xv[j] = xr[64 * j]; }
; #pragma unroll
;         for (int j = 0; j < 4; ++j)
; #pragma unroll
;             for (int k = 0; k < 4; ++k) { v[j][2 * k] = bflo(mv[j][k]); v[j][2 * k + 1] = bfhi(mv[j][k]); s += v[j][2 * k] * v[j][2 * k] + v[j][2 * k + 1] * v[j][2 * k + 1]; }
;         const float rs = rsqrtf(wave_sum(s) * (1.f / DM) + EPS);
.LBB0_1188:
	v_readlane_b32 s10, v253, 0
	v_readlane_b32 s11, v253, 1
	s_nop 1
	v_lshl_add_u64 v[38:39], s[10:11], 0, v[30:31]
	v_add_co_u32_e32 v58, vcc, 0xd400000, v38
	s_nop 1
	v_addc_co_u32_e32 v59, vcc, 0, v39, vcc
	s_waitcnt lgkmcnt(0)
	global_load_dwordx4 v[46:49], v[58:59], off
	global_load_dwordx4 v[50:53], v[58:59], off offset:1024
	global_load_dwordx4 v[54:57], v[58:59], off offset:2048
	s_nop 0
	global_load_dwordx4 v[58:61], v[58:59], off offset:3072
	v_add_co_u32_e32 v38, vcc, 0x9400000, v38
	s_waitcnt vmcnt(0)
	v_lshlrev_b32_e32 v79, 16, v47
	v_addc_co_u32_e32 v39, vcc, 0, v39, vcc
	global_load_dwordx4 v[62:65], v[38:39], off
	global_load_dwordx4 v[66:69], v[38:39], off offset:1024
	global_load_dwordx4 v[70:73], v[38:39], off offset:2048
	global_load_dwordx4 v[74:77], v[38:39], off offset:3072
	v_lshlrev_b32_e32 v78, 16, v46
	v_and_b32_e32 v47, 0xffff0000, v47
	v_and_b32_e32 v46, 0xffff0000, v46
	v_lshlrev_b32_e32 v81, 16, v49
	v_lshlrev_b32_e32 v80, 16, v48
	v_and_b32_e32 v49, 0xffff0000, v49
	v_and_b32_e32 v48, 0xffff0000, v48
	v_pk_mul_f32 v[94:95], v[46:47], v[46:47]
	v_pk_mul_f32 v[98:99], v[48:49], v[48:49]
	v_pk_fma_f32 v[94:95], v[78:79], v[78:79], v[94:95]
	v_lshlrev_b32_e32 v83, 16, v51
	v_lshlrev_b32_e32 v82, 16, v50
	v_and_b32_e32 v51, 0xffff0000, v51
	v_and_b32_e32 v50, 0xffff0000, v50
	v_pk_fma_f32 v[98:99], v[80:81], v[80:81], v[98:99]
	v_add_f32_e32 v94, v94, v95
	v_pk_mul_f32 v[102:103], v[50:51], v[50:51]
	v_add_f32_e32 v94, v98, v94
	v_lshlrev_b32_e32 v85, 16, v53
	v_lshlrev_b32_e32 v84, 16, v52
	v_and_b32_e32 v53, 0xffff0000, v53
	v_and_b32_e32 v52, 0xffff0000, v52
	v_pk_fma_f32 v[102:103], v[82:83], v[82:83], v[102:103]
	v_add_f32_e32 v94, v99, v94
	v_pk_mul_f32 v[104:105], v[52:53], v[52:53]
	v_add_f32_e32 v94, v102, v94
	v_lshlrev_b32_e32 v87, 16, v55
	v_lshlrev_b32_e32 v86, 16, v54
	v_and_b32_e32 v55, 0xffff0000, v55
	v_and_b32_e32 v54, 0xffff0000, v54
	v_pk_fma_f32 v[104:105], v[84:85], v[84:85], v[104:105]
	v_add_f32_e32 v94, v103, v94
	v_pk_mul_f32 v[106:107], v[54:55], v[54:55]
	v_add_f32_e32 v94, v104, v94
	v_lshlrev_b32_e32 v89, 16, v57
	v_lshlrev_b32_e32 v88, 16, v56
	v_and_b32_e32 v57, 0xffff0000, v57
	v_and_b32_e32 v56, 0xffff0000, v56
	v_pk_fma_f32 v[106:107], v[86:87], v[86:87], v[106:107]
	v_add_f32_e32 v94, v105, v94
	v_pk_mul_f32 v[108:109], v[56:57], v[56:57]
	v_add_f32_e32 v94, v106, v94
	v_lshlrev_b32_e32 v91, 16, v59
	v_lshlrev_b32_e32 v90, 16, v58
	v_and_b32_e32 v59, 0xffff0000, v59
	v_and_b32_e32 v58, 0xffff0000, v58
	v_pk_fma_f32 v[108:109], v[88:89], v[88:89], v[108:109]
	v_add_f32_e32 v94, v107, v94
	v_pk_mul_f32 v[110:111], v[58:59], v[58:59]
	v_add_f32_e32 v94, v108, v94
	v_lshlrev_b32_e32 v93, 16, v61
	v_lshlrev_b32_e32 v92, 16, v60
	v_and_b32_e32 v61, 0xffff0000, v61
	v_and_b32_e32 v60, 0xffff0000, v60
	v_pk_fma_f32 v[110:111], v[90:91], v[90:91], v[110:111]
	v_add_f32_e32 v94, v109, v94
	v_pk_mul_f32 v[112:113], v[60:61], v[60:61]
	v_add_f32_e32 v94, v110, v94
	v_pk_fma_f32 v[112:113], v[92:93], v[92:93], v[112:113]
	v_add_f32_e32 v94, v111, v94
	v_add_f32_e32 v94, v112, v94
	v_add_f32_e32 v94, v113, v94
	s_waitcnt lgkmcnt(0)
	s_nop 1
	v_add_f32_dpp v98, v94, v94 quad_perm:[1,0,3,2] row_mask:0xf bank_mask:0xf
	s_waitcnt lgkmcnt(0)
	s_nop 1
	v_add_f32_dpp v102, v98, v98 quad_perm:[2,3,0,1] row_mask:0xf bank_mask:0xf
	s_waitcnt vmcnt(3)
	v_lshlrev_b32_e32 v97, 16, v63
	v_lshlrev_b32_e32 v96, 16, v62
	v_and_b32_e32 v63, 0xffff0000, v63
	s_waitcnt lgkmcnt(0)
	s_nop 1
	v_add_f32_dpp v104, v102, v102 row_half_mirror row_mask:0xf bank_mask:0xf
	v_and_b32_e32 v62, 0xffff0000, v62
	v_lshlrev_b32_e32 v101, 16, v65
	v_lshlrev_b32_e32 v100, 16, v64
	v_and_b32_e32 v65, 0xffff0000, v65
	s_waitcnt lgkmcnt(0)
	s_nop 1
	v_add_f32_dpp v106, v104, v104 row_mirror row_mask:0xf bank_mask:0xf
	v_and_b32_e32 v64, 0xffff0000, v64
	s_waitcnt vmcnt(0)
	v_lshlrev_b32_e32 v109, 16, v77
	v_and_b32_e32 v77, 0xffff0000, v77
	v_lshlrev_b32_e32 v95, 16, v67
	s_waitcnt lgkmcnt(0)
	v_mov_b32_e32 v108, v106
	s_nop 1
	v_permlane16_swap_b32_e32 v108, v106
	v_add_f32_e32 v108, v108, v106
	v_lshlrev_b32_e32 v94, 16, v66
	v_and_b32_e32 v67, 0xffff0000, v67
	v_and_b32_e32 v66, 0xffff0000, v66
	v_lshlrev_b32_e32 v99, 16, v69
	s_waitcnt lgkmcnt(0)
; __device__ __forceinline__ unsigned pk2(float lo, float hi) { return f2bf(lo) | (f2bf(hi) << 16); }
; __device__ __forceinline__ void postnorm(const Ctx& c, const bf16* MF, bf16* XB, float* RS, const float* gpost, float* OUT) {
;     ...
;         const float rs = rsqrtf(wave_sum(s) * (1.f / DM) + EPS);
;         float s2 = 0.f;
; #pragma unroll
;         for (int j = 0; j < 4; ++j) { const float* gp = gpost + (c.lane + 64 * j) * 8; const f32x4 g0 = *(CF4)gp, g1 = *(CF4)(gp + 4);
; #pragma unroll
;             for (int k = 0; k < 4; ++k) { const float ga = (k < 2) ? g0[2 * k] : g1[2 * k - 4], gb = (k < 2) ? g0[2 * k + 1] : g1[2 * k - 3];
;                 v[j][2 * k] = bflo(xv[j][k]) + v[j][2 * k] * rs * ga; v[j][2 * k + 1] = bfhi(xv[j][k]) + v[j][2 * k + 1] * rs * gb;
;                 s2 += v[j][2 * k] * v[j][2 * k] + v[j][2 * k + 1] * v[j][2 * k + 1]; } }
;         if (OUT) {
; #pragma unroll
;             for (int j = 0; j < 4; ++j) { float* op = OUT + (size_t)row * DM + (c.lane + 64 * j) * 8; *(f32x4*)op = (f32x4){v[j][0], v[j][1], v[j][2], v[j][3]}; *(f32x4*)(op + 4) = (f32x4){v[j][4], v[j][5], v[j][6], v[j][7]}; }
;         } else {
; #pragma unroll
;             for (int j = 0; j < 4; ++j) { v4u o; o.x = pk2(v[j][0], v[j][1]); o.y = pk2(v[j][2], v[j][3]); o.z = pk2(v[j][4], v[j][5]); o.w = pk2(v[j][6], v[j][7]); xr[64 * j] = o; }
;             const float rs2 = rsqrtf(wave_sum(s2) * (1.f / DM) + EPS); if (c.lane == 0) RS[row] = rs2;
	v_mov_b32_e32 v110, v108
	s_nop 1
	v_permlane32_swap_b32_e32 v108, v110
	v_add_f32_e32 v108, v108, v110
	v_fmamk_f32 v108, v108, 0x3a000000, v45
	v_mul_f32_e32 v110, 0x4b800000, v108
	v_cmp_gt_f32_e32 vcc, s15, v108
	v_lshlrev_b32_e32 v98, 16, v68
	v_and_b32_e32 v69, 0xffff0000, v69
	v_cndmask_b32_e32 v108, v108, v110, vcc
	v_rsq_f32_e32 v110, v108
	v_lshlrev_b32_e32 v108, 16, v76
	v_and_b32_e32 v76, 0xffff0000, v76
	v_and_b32_e32 v68, 0xffff0000, v68
	v_mul_f32_e32 v111, 0x45800000, v110
	v_cndmask_b32_e32 v110, v110, v111, vcc
	v_pk_mul_f32 v[46:47], v[110:111], v[46:47] op_sel_hi:[0,1]
	v_pk_mul_f32 v[78:79], v[110:111], v[78:79] op_sel_hi:[0,1]
	v_pk_mul_f32 v[48:49], v[110:111], v[48:49] op_sel_hi:[0,1]
	v_pk_fma_f32 v[46:47], v[36:37], v[46:47], v[62:63]
	v_pk_mul_f32 v[60:61], v[110:111], v[60:61] op_sel_hi:[0,1]
	v_pk_mul_f32 v[80:81], v[110:111], v[80:81] op_sel_hi:[0,1]
	v_pk_fma_f32 v[78:79], v[8:9], v[78:79], v[96:97]
	v_pk_fma_f32 v[48:49], v[10:11], v[48:49], v[64:65]
	v_pk_fma_f32 v[60:61], v[34:35], v[60:61], v[76:77]
	v_pk_mul_f32 v[76:77], v[46:47], v[46:47]
	v_pk_mul_f32 v[50:51], v[110:111], v[50:51] op_sel_hi:[0,1]
	v_pk_fma_f32 v[62:63], v[4:5], v[80:81], v[100:101]
	v_pk_fma_f32 v[76:77], v[78:79], v[78:79], v[76:77]
	v_pk_mul_f32 v[80:81], v[48:49], v[48:49]
	v_pk_mul_f32 v[82:83], v[110:111], v[82:83] op_sel_hi:[0,1]
	v_pk_fma_f32 v[50:51], v[6:7], v[50:51], v[66:67]
	v_pk_fma_f32 v[80:81], v[62:63], v[62:63], v[80:81]
	v_add_f32_e32 v76, v76, v77
	v_pk_fma_f32 v[64:65], v[16:17], v[82:83], v[94:95]
	v_pk_mul_f32 v[82:83], v[50:51], v[50:51]
	v_add_f32_e32 v76, v80, v76
	v_pk_fma_f32 v[82:83], v[64:65], v[64:65], v[82:83]
	v_add_f32_e32 v76, v81, v76
	v_add_f32_e32 v76, v82, v76
	s_nop 2
	v_bfe_u32 v82, v46, 16, 1
	v_pk_mul_f32 v[52:53], v[110:111], v[52:53] op_sel_hi:[0,1]
	v_add3_u32 v46, v46, v82, s16
	s_nop 2
	v_bfe_u32 v77, v78, 16, 1
	s_nop 2
	v_pk_mul_f32 v[84:85], v[110:111], v[84:85] op_sel_hi:[0,1]
	v_pk_fma_f32 v[52:53], v[18:19], v[52:53], v[68:69]
	s_nop 2
	v_add3_u32 v77, v78, v77, s16
	v_lshlrev_b32_e32 v103, 16, v71
	v_lshlrev_b32_e32 v102, 16, v70
	v_and_b32_e32 v71, 0xffff0000, v71
	v_and_b32_e32 v70, 0xffff0000, v70
	v_pk_fma_f32 v[66:67], v[12:13], v[84:85], v[98:99]
	v_pk_mul_f32 v[54:55], v[110:111], v[54:55] op_sel_hi:[0,1]
	v_pk_mul_f32 v[84:85], v[52:53], v[52:53]
	v_lshrrev_b32_e32 v77, 16, v77
	s_nop 2
	v_pk_mul_f32 v[68:69], v[110:111], v[86:87] op_sel_hi:[0,1]
	v_pk_fma_f32 v[54:55], v[14:15], v[54:55], v[70:71]
	v_pk_fma_f32 v[84:85], v[66:67], v[66:67], v[84:85]
	v_add_f32_e32 v76, v83, v76
	v_cvt_pk_bf16_f32 v49, v63, v49
	v_cvt_pk_bf16_f32 v48, v62, v48
	v_cvt_pk_bf16_f32 v47, v79, v47
	v_and_or_b32 v46, v46, s14, v77
	v_lshlrev_b32_e32 v105, 16, v73
	v_lshlrev_b32_e32 v104, 16, v72
	v_and_b32_e32 v73, 0xffff0000, v73
	v_and_b32_e32 v72, 0xffff0000, v72
	v_pk_fma_f32 v[68:69], v[24:25], v[68:69], v[102:103]
	v_pk_mul_f32 v[56:57], v[110:111], v[56:57] op_sel_hi:[0,1]
	v_pk_mul_f32 v[86:87], v[54:55], v[54:55]
	v_add_f32_e32 v76, v84, v76
	global_store_dwordx4 v[38:39], v[46:49], off
	v_pk_mul_f32 v[70:71], v[110:111], v[88:89] op_sel_hi:[0,1]
	v_pk_fma_f32 v[56:57], v[26:27], v[56:57], v[72:73]
	s_nop 3
	v_pk_fma_f32 v[86:87], v[68:69], v[68:69], v[86:87]
	v_add_f32_e32 v76, v85, v76
	s_nop 7
	v_lshlrev_b32_e32 v107, 16, v75
	v_lshlrev_b32_e32 v106, 16, v74
	v_and_b32_e32 v75, 0xffff0000, v75
	v_and_b32_e32 v74, 0xffff0000, v74
	v_pk_fma_f32 v[70:71], v[20:21], v[70:71], v[104:105]
	v_pk_mul_f32 v[58:59], v[110:111], v[58:59] op_sel_hi:[0,1]
	v_pk_mul_f32 v[88:89], v[56:57], v[56:57]
	v_add_f32_e32 v76, v86, v76
	s_nop 3
	v_pk_mul_f32 v[72:73], v[110:111], v[90:91] op_sel_hi:[0,1]
	v_pk_fma_f32 v[58:59], v[22:23], v[58:59], v[74:75]
	v_pk_fma_f32 v[88:89], v[70:71], v[70:71], v[88:89]
	v_add_f32_e32 v76, v87, v76
	s_nop 3
	v_pk_fma_f32 v[72:73], v[32:33], v[72:73], v[106:107]
	v_pk_mul_f32 v[90:91], v[58:59], v[58:59]
	v_add_f32_e32 v76, v88, v76
	v_cvt_pk_bf16_f32 v49, v67, v53
	v_cvt_pk_bf16_f32 v48, v66, v52
	v_cvt_pk_bf16_f32 v47, v65, v51
	v_cvt_pk_bf16_f32 v46, v64, v50
	v_pk_mul_f32 v[74:75], v[110:111], v[92:93] op_sel_hi:[0,1]
	v_pk_fma_f32 v[90:91], v[72:73], v[72:73], v[90:91]
	v_add_f32_e32 v76, v89, v76
	global_store_dwordx4 v[38:39], v[46:49], off offset:1024
	v_pk_fma_f32 v[74:75], v[28:29], v[74:75], v[108:109]
	v_pk_mul_f32 v[92:93], v[60:61], v[60:61]
	s_nop 1
	v_add_f32_e32 v76, v90, v76
	s_nop 5
	v_pk_fma_f32 v[92:93], v[74:75], v[74:75], v[92:93]
	v_add_f32_e32 v76, v91, v76
	s_nop 5
	v_add_f32_e32 v76, v92, v76
	s_nop 5
	v_add_f32_e32 v76, v93, v76
	v_cvt_pk_bf16_f32 v49, v71, v57
	v_cvt_pk_bf16_f32 v48, v70, v56
	v_cvt_pk_bf16_f32 v47, v69, v55
	v_cvt_pk_bf16_f32 v46, v68, v54
	global_store_dwordx4 v[38:39], v[46:49], off offset:2048
	s_nop 3
	s_waitcnt lgkmcnt(0)
	s_nop 1
	v_add_f32_dpp v47, v76, v76 quad_perm:[1,0,3,2] row_mask:0xf bank_mask:0xf
	s_nop 3
	s_waitcnt lgkmcnt(0)
	s_nop 1
	v_add_f32_dpp v47, v47, v47 quad_perm:[2,3,0,1] row_mask:0xf bank_mask:0xf
	s_nop 1
	v_cvt_pk_bf16_f32 v51, v75, v61
	s_nop 0
	s_waitcnt lgkmcnt(0)
	s_nop 1
	v_add_f32_dpp v47, v47, v47 row_half_mirror row_mask:0xf bank_mask:0xf
	s_nop 3
	s_waitcnt lgkmcnt(0)
	s_nop 1
	v_add_f32_dpp v47, v47, v47 row_mirror row_mask:0xf bank_mask:0xf
	s_nop 3
	s_waitcnt lgkmcnt(0)
	v_mov_b32_e32 v50, v47
	v_mov_b32_e32 v46, v47
	s_nop 1
	v_permlane16_swap_b32_e32 v46, v50
	v_add_f32_e32 v46, v46, v50
	ds_bpermute_b32 v47, v44, v46
	s_nop 0
	v_cvt_pk_bf16_f32 v50, v74, v60
	v_cvt_pk_bf16_f32 v49, v73, v59
	v_cvt_pk_bf16_f32 v48, v72, v58
	global_store_dwordx4 v[38:39], v[48:51], off offset:3072
	s_and_saveexec_b64 s[10:11], s[0:1]
	s_cbranch_execz .LBB0_1187
	s_waitcnt lgkmcnt(0)
	v_add_f32_e32 v38, v46, v47
	v_fmamk_f32 v38, v38, 0x3a000000, v45
	v_mul_f32_e32 v39, 0x4b800000, v38
	v_cmp_gt_f32_e32 vcc, s15, v38
	v_readlane_b32 s18, v253, 0
	v_readlane_b32 s19, v253, 1
	v_cndmask_b32_e32 v38, v38, v39, vcc
	v_rsq_f32_e32 v38, v38
	s_add_u32 s18, s18, s12
	s_addc_u32 s19, s19, s13
	v_mul_f32_e32 v39, 0x45800000, v38
	v_cndmask_b32_e32 v38, v38, v39, vcc
	global_store_dword v251, v38, s[18:19]
	s_branch .LBB0_1187

; __device__ __forceinline__ float wave_sum(float v) {
; #pragma unroll
;     for (int o = 1; o < 64; o <<= 1) v += __shfl_xor(v, o);
;     return v;
; __device__ __forceinline__ void postnorm(const Ctx& c, const bf16* MF, bf16* XB, float* RS, const float* gpost, float* OUT) {
;     ...
;         const v4u* mr = (const v4u*)(MF + (size_t)row * DM) + c.lane; v4u* xr = (v4u*)(XB + (size_t)row * DM) + c.lane;
;         v4u mv[4], xv[4]; float v[4][8]; float s = 0.f;
; #pragma unroll
;         for (int j = 0; j < 4; ++j) { mv[j] = mr[64 * j]; xv[j] = xr[64 * j]; }
; #pragma unroll
;         for (int j = 0; j < 4; ++j)
; #pragma unroll
;             for (int k = 0; k < 4; ++k) { v[j][2 * k] = bflo(mv[j][k]); v[j][2 * k + 1] = bfhi(mv[j][k]); s += v[j][2 * k] * v[j][2 * k] + v[j][2 * k + 1] * v[j][2 * k + 1]; }
;         const float rs = rsqrtf(wave_sum(s) * (1.f / DM) + EPS);
.LBB0_1474:
	v_readlane_b32 s8, v253, 0
	v_readlane_b32 s9, v253, 1
	s_nop 1
	v_lshl_add_u64 v[38:39], s[8:9], 0, v[30:31]
	v_add_co_u32_e32 v58, vcc, 0xd400000, v38
	s_nop 1
	v_addc_co_u32_e32 v59, vcc, 0, v39, vcc
	s_waitcnt lgkmcnt(0)
	global_load_dwordx4 v[46:49], v[58:59], off
	global_load_dwordx4 v[50:53], v[58:59], off offset:1024
	global_load_dwordx4 v[54:57], v[58:59], off offset:2048
	s_nop 0
	global_load_dwordx4 v[58:61], v[58:59], off offset:3072
	v_add_co_u32_e32 v38, vcc, 0x9400000, v38
	s_waitcnt vmcnt(3)
	v_lshlrev_b32_e32 v79, 16, v47
	v_addc_co_u32_e32 v39, vcc, 0, v39, vcc
	global_load_dwordx4 v[62:65], v[38:39], off
	global_load_dwordx4 v[66:69], v[38:39], off offset:1024
	global_load_dwordx4 v[70:73], v[38:39], off offset:2048
	global_load_dwordx4 v[74:77], v[38:39], off offset:3072
	v_lshlrev_b32_e32 v78, 16, v46
	v_and_b32_e32 v47, 0xffff0000, v47
	v_and_b32_e32 v46, 0xffff0000, v46
	v_lshlrev_b32_e32 v81, 16, v49
	v_lshlrev_b32_e32 v80, 16, v48
	v_and_b32_e32 v49, 0xffff0000, v49
	v_and_b32_e32 v48, 0xffff0000, v48
	v_pk_mul_f32 v[94:95], v[46:47], v[46:47]
	v_pk_mul_f32 v[98:99], v[48:49], v[48:49]
	v_pk_fma_f32 v[94:95], v[78:79], v[78:79], v[94:95]
	s_waitcnt vmcnt(6)
	v_lshlrev_b32_e32 v83, 16, v51
	v_lshlrev_b32_e32 v82, 16, v50
	v_and_b32_e32 v51, 0xffff0000, v51
	v_and_b32_e32 v50, 0xffff0000, v50
	v_pk_fma_f32 v[98:99], v[80:81], v[80:81], v[98:99]
	v_add_f32_e32 v94, v94, v95
	v_pk_mul_f32 v[102:103], v[50:51], v[50:51]
	v_add_f32_e32 v94, v98, v94
	v_lshlrev_b32_e32 v85, 16, v53
	v_lshlrev_b32_e32 v84, 16, v52
	v_and_b32_e32 v53, 0xffff0000, v53
	v_and_b32_e32 v52, 0xffff0000, v52
	v_pk_fma_f32 v[102:103], v[82:83], v[82:83], v[102:103]
	v_add_f32_e32 v94, v99, v94
	v_pk_mul_f32 v[104:105], v[52:53], v[52:53]
	v_add_f32_e32 v94, v102, v94
	s_waitcnt vmcnt(5)
	v_lshlrev_b32_e32 v87, 16, v55
	v_lshlrev_b32_e32 v86, 16, v54
	v_and_b32_e32 v55, 0xffff0000, v55
	v_and_b32_e32 v54, 0xffff0000, v54
	v_pk_fma_f32 v[104:105], v[84:85], v[84:85], v[104:105]
	v_add_f32_e32 v94, v103, v94
	v_pk_mul_f32 v[106:107], v[54:55], v[54:55]
	v_add_f32_e32 v94, v104, v94
	v_lshlrev_b32_e32 v89, 16, v57
	v_lshlrev_b32_e32 v88, 16, v56
	v_and_b32_e32 v57, 0xffff0000, v57
	v_and_b32_e32 v56, 0xffff0000, v56
	v_pk_fma_f32 v[106:107], v[86:87], v[86:87], v[106:107]
	v_add_f32_e32 v94, v105, v94
	v_pk_mul_f32 v[108:109], v[56:57], v[56:57]
	v_add_f32_e32 v94, v106, v94
	s_waitcnt vmcnt(4)
	v_lshlrev_b32_e32 v91, 16, v59
	v_lshlrev_b32_e32 v90, 16, v58
	v_and_b32_e32 v59, 0xffff0000, v59
	v_and_b32_e32 v58, 0xffff0000, v58
	v_pk_fma_f32 v[108:109], v[88:89], v[88:89], v[108:109]
	v_add_f32_e32 v94, v107, v94
	v_pk_mul_f32 v[110:111], v[58:59], v[58:59]
	v_add_f32_e32 v94, v108, v94
	v_lshlrev_b32_e32 v93, 16, v61
	v_lshlrev_b32_e32 v92, 16, v60
	v_and_b32_e32 v61, 0xffff0000, v61
	v_and_b32_e32 v60, 0xffff0000, v60
	v_pk_fma_f32 v[110:111], v[90:91], v[90:91], v[110:111]
	v_add_f32_e32 v94, v109, v94
	v_pk_mul_f32 v[112:113], v[60:61], v[60:61]
	v_add_f32_e32 v94, v110, v94
	v_pk_fma_f32 v[112:113], v[92:93], v[92:93], v[112:113]
	v_add_f32_e32 v94, v111, v94
	v_add_f32_e32 v94, v112, v94
	v_add_f32_e32 v94, v113, v94
	s_waitcnt lgkmcnt(0)
	s_nop 1
	v_add_f32_dpp v98, v94, v94 quad_perm:[1,0,3,2] row_mask:0xf bank_mask:0xf
	s_waitcnt lgkmcnt(0)
	s_nop 1
	v_add_f32_dpp v102, v98, v98 quad_perm:[2,3,0,1] row_mask:0xf bank_mask:0xf
	s_waitcnt vmcnt(3)
	v_lshlrev_b32_e32 v97, 16, v63
	v_lshlrev_b32_e32 v96, 16, v62
	v_and_b32_e32 v63, 0xffff0000, v63
	s_waitcnt lgkmcnt(0)
	s_nop 1
	v_add_f32_dpp v104, v102, v102 row_half_mirror row_mask:0xf bank_mask:0xf
	v_and_b32_e32 v62, 0xffff0000, v62
	v_lshlrev_b32_e32 v101, 16, v65
	v_lshlrev_b32_e32 v100, 16, v64
	v_and_b32_e32 v65, 0xffff0000, v65
	s_waitcnt lgkmcnt(0)
	s_nop 1
	v_add_f32_dpp v106, v104, v104 row_mirror row_mask:0xf bank_mask:0xf
	v_and_b32_e32 v64, 0xffff0000, v64
	s_waitcnt vmcnt(0)
	v_lshlrev_b32_e32 v109, 16, v77
	v_and_b32_e32 v77, 0xffff0000, v77
	v_lshlrev_b32_e32 v95, 16, v67
	s_waitcnt lgkmcnt(0)
	v_mov_b32_e32 v108, v106
	s_nop 1
	v_permlane16_swap_b32_e32 v108, v106
	v_add_f32_e32 v108, v108, v106
	v_lshlrev_b32_e32 v94, 16, v66
	v_and_b32_e32 v67, 0xffff0000, v67
	v_and_b32_e32 v66, 0xffff0000, v66
	v_lshlrev_b32_e32 v99, 16, v69
	s_waitcnt lgkmcnt(0)
; __device__ __forceinline__ unsigned pk2(float lo, float hi) { return f2bf(lo) | (f2bf(hi) << 16); }
; __device__ __forceinline__ void postnorm(const Ctx& c, const bf16* MF, bf16* XB, float* RS, const float* gpost, float* OUT) {
;     ...
;         const float rs = rsqrtf(wave_sum(s) * (1.f / DM) + EPS);
;         float s2 = 0.f;
; #pragma unroll
;         for (int j = 0; j < 4; ++j) { const float* gp = gpost + (c.lane + 64 * j) * 8; const f32x4 g0 = *(CF4)gp, g1 = *(CF4)(gp + 4);
; #pragma unroll
;             for (int k = 0; k < 4; ++k) { const float ga = (k < 2) ? g0[2 * k] : g1[2 * k - 4], gb = (k < 2) ? g0[2 * k + 1] : g1[2 * k - 3];
;                 v[j][2 * k] = bflo(xv[j][k]) + v[j][2 * k] * rs * ga; v[j][2 * k + 1] = bfhi(xv[j][k]) + v[j][2 * k + 1] * rs * gb;
;                 s2 += v[j][2 * k] * v[j][2 * k] + v[j][2 * k + 1] * v[j][2 * k + 1]; } }
;         if (OUT) {
; #pragma unroll
;             for (int j = 0; j < 4; ++j) { float* op = OUT + (size_t)row * DM + (c.lane + 64 * j) * 8; *(f32x4*)op = (f32x4){v[j][0], v[j][1], v[j][2], v[j][3]}; *(f32x4*)(op + 4) = (f32x4){v[j][4], v[j][5], v[j][6], v[j][7]}; }
;         } else {
; #pragma unroll
;             for (int j = 0; j < 4; ++j) { v4u o; o.x = pk2(v[j][0], v[j][1]); o.y = pk2(v[j][2], v[j][3]); o.z = pk2(v[j][4], v[j][5]); o.w = pk2(v[j][6], v[j][7]); xr[64 * j] = o; }
;             const float rs2 = rsqrtf(wave_sum(s2) * (1.f / DM) + EPS); if (c.lane == 0) RS[row] = rs2;
	v_mov_b32_e32 v110, v108
	s_nop 1
	v_permlane32_swap_b32_e32 v108, v110
	v_add_f32_e32 v108, v108, v110
	v_fmamk_f32 v108, v108, 0x3a000000, v45
	v_mul_f32_e32 v110, 0x4b800000, v108
	v_cmp_gt_f32_e32 vcc, s13, v108
	v_lshlrev_b32_e32 v98, 16, v68
	v_and_b32_e32 v69, 0xffff0000, v69
	v_cndmask_b32_e32 v108, v108, v110, vcc
	v_rsq_f32_e32 v110, v108
	v_lshlrev_b32_e32 v108, 16, v76
	v_and_b32_e32 v76, 0xffff0000, v76
	v_and_b32_e32 v68, 0xffff0000, v68
	v_mul_f32_e32 v111, 0x45800000, v110
	v_cndmask_b32_e32 v110, v110, v111, vcc
	v_pk_mul_f32 v[46:47], v[110:111], v[46:47] op_sel_hi:[0,1]
	v_pk_mul_f32 v[78:79], v[110:111], v[78:79] op_sel_hi:[0,1]
	v_pk_mul_f32 v[48:49], v[110:111], v[48:49] op_sel_hi:[0,1]
	v_pk_fma_f32 v[46:47], v[36:37], v[46:47], v[62:63]
	v_pk_mul_f32 v[60:61], v[110:111], v[60:61] op_sel_hi:[0,1]
	v_pk_mul_f32 v[80:81], v[110:111], v[80:81] op_sel_hi:[0,1]
	v_pk_fma_f32 v[78:79], v[8:9], v[78:79], v[96:97]
	v_pk_fma_f32 v[48:49], v[10:11], v[48:49], v[64:65]
	v_pk_fma_f32 v[60:61], v[34:35], v[60:61], v[76:77]
	v_pk_mul_f32 v[76:77], v[46:47], v[46:47]
	v_pk_mul_f32 v[50:51], v[110:111], v[50:51] op_sel_hi:[0,1]
	v_pk_fma_f32 v[62:63], v[4:5], v[80:81], v[100:101]
	v_pk_fma_f32 v[76:77], v[78:79], v[78:79], v[76:77]
	v_pk_mul_f32 v[80:81], v[48:49], v[48:49]
	v_pk_mul_f32 v[82:83], v[110:111], v[82:83] op_sel_hi:[0,1]
	v_pk_fma_f32 v[50:51], v[6:7], v[50:51], v[66:67]
	v_pk_fma_f32 v[80:81], v[62:63], v[62:63], v[80:81]
	v_add_f32_e32 v76, v76, v77
	v_pk_fma_f32 v[64:65], v[16:17], v[82:83], v[94:95]
	v_pk_mul_f32 v[82:83], v[50:51], v[50:51]
	v_add_f32_e32 v76, v80, v76
	v_pk_fma_f32 v[82:83], v[64:65], v[64:65], v[82:83]
	v_add_f32_e32 v76, v81, v76
	v_add_f32_e32 v76, v82, v76
	s_nop 2
	v_bfe_u32 v82, v46, 16, 1
	v_pk_mul_f32 v[52:53], v[110:111], v[52:53] op_sel_hi:[0,1]
	v_add3_u32 v46, v46, v82, s14
	s_nop 2
	v_bfe_u32 v77, v78, 16, 1
	s_nop 2
	v_pk_mul_f32 v[84:85], v[110:111], v[84:85] op_sel_hi:[0,1]
	v_pk_fma_f32 v[52:53], v[18:19], v[52:53], v[68:69]
	s_nop 2
	v_add3_u32 v77, v78, v77, s14
	v_lshlrev_b32_e32 v103, 16, v71
	v_lshlrev_b32_e32 v102, 16, v70
	v_and_b32_e32 v71, 0xffff0000, v71
	v_and_b32_e32 v70, 0xffff0000, v70
	v_pk_fma_f32 v[66:67], v[12:13], v[84:85], v[98:99]
	v_pk_mul_f32 v[54:55], v[110:111], v[54:55] op_sel_hi:[0,1]
	v_pk_mul_f32 v[84:85], v[52:53], v[52:53]
	v_lshrrev_b32_e32 v77, 16, v77
	s_nop 2
	v_pk_mul_f32 v[68:69], v[110:111], v[86:87] op_sel_hi:[0,1]
	v_pk_fma_f32 v[54:55], v[14:15], v[54:55], v[70:71]
	v_pk_fma_f32 v[84:85], v[66:67], v[66:67], v[84:85]
	v_add_f32_e32 v76, v83, v76
	v_cvt_pk_bf16_f32 v49, v63, v49
	v_cvt_pk_bf16_f32 v48, v62, v48
	v_cvt_pk_bf16_f32 v47, v79, v47
	v_and_or_b32 v46, v46, s12, v77
	v_lshlrev_b32_e32 v105, 16, v73
	v_lshlrev_b32_e32 v104, 16, v72
	v_and_b32_e32 v73, 0xffff0000, v73
	v_and_b32_e32 v72, 0xffff0000, v72
	v_pk_fma_f32 v[68:69], v[24:25], v[68:69], v[102:103]
	v_pk_mul_f32 v[56:57], v[110:111], v[56:57] op_sel_hi:[0,1]
	v_pk_mul_f32 v[86:87], v[54:55], v[54:55]
	v_add_f32_e32 v76, v84, v76
	global_store_dwordx4 v[38:39], v[46:49], off
	v_pk_mul_f32 v[70:71], v[110:111], v[88:89] op_sel_hi:[0,1]
	v_pk_fma_f32 v[56:57], v[26:27], v[56:57], v[72:73]
	s_nop 3
	v_pk_fma_f32 v[86:87], v[68:69], v[68:69], v[86:87]
	v_add_f32_e32 v76, v85, v76
	s_nop 7
	v_lshlrev_b32_e32 v107, 16, v75
	v_lshlrev_b32_e32 v106, 16, v74
	v_and_b32_e32 v75, 0xffff0000, v75
	v_and_b32_e32 v74, 0xffff0000, v74
	v_pk_fma_f32 v[70:71], v[20:21], v[70:71], v[104:105]
	v_pk_mul_f32 v[58:59], v[110:111], v[58:59] op_sel_hi:[0,1]
	v_pk_mul_f32 v[88:89], v[56:57], v[56:57]
	v_add_f32_e32 v76, v86, v76
	s_nop 3
	v_pk_mul_f32 v[72:73], v[110:111], v[90:91] op_sel_hi:[0,1]
	v_pk_fma_f32 v[58:59], v[22:23], v[58:59], v[74:75]
	v_pk_fma_f32 v[88:89], v[70:71], v[70:71], v[88:89]
	v_add_f32_e32 v76, v87, v76
	s_nop 3
	v_pk_fma_f32 v[72:73], v[32:33], v[72:73], v[106:107]
	v_pk_mul_f32 v[90:91], v[58:59], v[58:59]
	v_add_f32_e32 v76, v88, v76
	v_cvt_pk_bf16_f32 v49, v67, v53
	v_cvt_pk_bf16_f32 v48, v66, v52
	v_cvt_pk_bf16_f32 v47, v65, v51
	v_cvt_pk_bf16_f32 v46, v64, v50
	v_pk_mul_f32 v[74:75], v[110:111], v[92:93] op_sel_hi:[0,1]
	v_pk_fma_f32 v[90:91], v[72:73], v[72:73], v[90:91]
	v_add_f32_e32 v76, v89, v76
	global_store_dwordx4 v[38:39], v[46:49], off offset:1024
	v_pk_fma_f32 v[74:75], v[28:29], v[74:75], v[108:109]
	v_pk_mul_f32 v[92:93], v[60:61], v[60:61]
	s_nop 1
	v_add_f32_e32 v76, v90, v76
	s_nop 5
	v_pk_fma_f32 v[92:93], v[74:75], v[74:75], v[92:93]
	v_add_f32_e32 v76, v91, v76
	s_nop 5
	v_add_f32_e32 v76, v92, v76
	s_nop 5
	v_add_f32_e32 v76, v93, v76
	v_cvt_pk_bf16_f32 v49, v71, v57
	v_cvt_pk_bf16_f32 v48, v70, v56
	v_cvt_pk_bf16_f32 v47, v69, v55
	v_cvt_pk_bf16_f32 v46, v68, v54
	global_store_dwordx4 v[38:39], v[46:49], off offset:2048
	s_nop 3
	s_waitcnt lgkmcnt(0)
	s_nop 1
	v_add_f32_dpp v47, v76, v76 quad_perm:[1,0,3,2] row_mask:0xf bank_mask:0xf
	s_nop 3
	s_waitcnt lgkmcnt(0)
	s_nop 1
	v_add_f32_dpp v47, v47, v47 quad_perm:[2,3,0,1] row_mask:0xf bank_mask:0xf
	s_nop 1
	v_cvt_pk_bf16_f32 v51, v75, v61
	s_nop 0
	s_waitcnt lgkmcnt(0)
	s_nop 1
	v_add_f32_dpp v47, v47, v47 row_half_mirror row_mask:0xf bank_mask:0xf
	s_nop 3
	s_waitcnt lgkmcnt(0)
	s_nop 1
	v_add_f32_dpp v47, v47, v47 row_mirror row_mask:0xf bank_mask:0xf
	s_nop 3
	s_waitcnt lgkmcnt(0)
	v_mov_b32_e32 v50, v47
	v_mov_b32_e32 v46, v47
	s_nop 1
	v_permlane16_swap_b32_e32 v46, v50
	v_add_f32_e32 v46, v46, v50
	ds_bpermute_b32 v47, v44, v46
	s_nop 0
	v_cvt_pk_bf16_f32 v50, v74, v60
	v_cvt_pk_bf16_f32 v49, v73, v59
	v_cvt_pk_bf16_f32 v48, v72, v58
	global_store_dwordx4 v[38:39], v[48:51], off offset:3072
	s_and_saveexec_b64 s[8:9], s[0:1]
	s_cbranch_execz .LBB0_1473
	s_waitcnt lgkmcnt(0)
	v_add_f32_e32 v38, v46, v47
	v_fmamk_f32 v38, v38, 0x3a000000, v45
	v_mul_f32_e32 v39, 0x4b800000, v38
	v_cmp_gt_f32_e32 vcc, s13, v38
	v_readlane_b32 s16, v253, 0
	v_readlane_b32 s17, v253, 1
	v_cndmask_b32_e32 v38, v38, v39, vcc
	v_rsq_f32_e32 v38, v38
	s_add_u32 s16, s16, s10
	s_addc_u32 s17, s17, s11
	v_mul_f32_e32 v39, 0x45800000, v38
	v_cndmask_b32_e32 v38, v38, v39, vcc
	global_store_dword v251, v38, s[16:17]
	s_branch .LBB0_1473

; __device__ __forceinline__ float wave_sum(float v) {
; #pragma unroll
;     for (int o = 1; o < 64; o <<= 1) v += __shfl_xor(v, o);
;     return v;
; __device__ __forceinline__ void postnorm(const Ctx& c, const bf16* MF, bf16* XB, float* RS, const float* gpost, float* OUT) {
;     ...
;         const v4u* mr = (const v4u*)(MF + (size_t)row * DM) + c.lane; v4u* xr = (v4u*)(XB + (size_t)row * DM) + c.lane;
;         v4u mv[4], xv[4]; float v[4][8]; float s = 0.f;
; #pragma unroll
;         for (int j = 0; j < 4; ++j) { mv[j] = mr[64 * j]; xv[j] = xr[64 * j]; }
; #pragma unroll
;         for (int j = 0; j < 4; ++j)
; #pragma unroll
;             for (int k = 0; k < 4; ++k) { v[j][2 * k] = bflo(mv[j][k]); v[j][2 * k + 1] = bfhi(mv[j][k]); s += v[j][2 * k] * v[j][2 * k] + v[j][2 * k + 1] * v[j][2 * k + 1]; }
;         const float rs = rsqrtf(wave_sum(s) * (1.f / DM) + EPS);
.LBB0_2484:
	v_readlane_b32 s12, v253, 0
	v_readlane_b32 s13, v253, 1
	s_nop 1
	v_lshl_add_u64 v[38:39], s[12:13], 0, v[30:31]
	v_add_co_u32_e32 v58, vcc, 0xd400000, v38
	s_nop 1
	v_addc_co_u32_e32 v59, vcc, 0, v39, vcc
	s_waitcnt lgkmcnt(0)
	global_load_dwordx4 v[46:49], v[58:59], off
	global_load_dwordx4 v[50:53], v[58:59], off offset:1024
	global_load_dwordx4 v[54:57], v[58:59], off offset:2048
	s_nop 0
	global_load_dwordx4 v[58:61], v[58:59], off offset:3072
	v_add_co_u32_e32 v38, vcc, 0x9400000, v38
	s_waitcnt vmcnt(3)
	v_lshlrev_b32_e32 v79, 16, v47
	v_addc_co_u32_e32 v39, vcc, 0, v39, vcc
	global_load_dwordx4 v[62:65], v[38:39], off
	global_load_dwordx4 v[66:69], v[38:39], off offset:1024
	global_load_dwordx4 v[70:73], v[38:39], off offset:2048
	global_load_dwordx4 v[74:77], v[38:39], off offset:3072
	v_lshlrev_b32_e32 v78, 16, v46
	v_and_b32_e32 v47, 0xffff0000, v47
	v_and_b32_e32 v46, 0xffff0000, v46
	v_lshlrev_b32_e32 v81, 16, v49
	v_lshlrev_b32_e32 v80, 16, v48
	v_and_b32_e32 v49, 0xffff0000, v49
	v_and_b32_e32 v48, 0xffff0000, v48
	v_pk_mul_f32 v[94:95], v[46:47], v[46:47]
	v_pk_mul_f32 v[98:99], v[48:49], v[48:49]
	v_pk_fma_f32 v[94:95], v[78:79], v[78:79], v[94:95]
	s_waitcnt vmcnt(6)
	v_lshlrev_b32_e32 v83, 16, v51
	v_lshlrev_b32_e32 v82, 16, v50
	v_and_b32_e32 v51, 0xffff0000, v51
	v_and_b32_e32 v50, 0xffff0000, v50
	v_pk_fma_f32 v[98:99], v[80:81], v[80:81], v[98:99]
	v_add_f32_e32 v94, v94, v95
	v_pk_mul_f32 v[102:103], v[50:51], v[50:51]
	v_add_f32_e32 v94, v98, v94
	v_lshlrev_b32_e32 v85, 16, v53
	v_lshlrev_b32_e32 v84, 16, v52
	v_and_b32_e32 v53, 0xffff0000, v53
	v_and_b32_e32 v52, 0xffff0000, v52
	v_pk_fma_f32 v[102:103], v[82:83], v[82:83], v[102:103]
	v_add_f32_e32 v94, v99, v94
	v_pk_mul_f32 v[104:105], v[52:53], v[52:53]
	v_add_f32_e32 v94, v102, v94
	s_waitcnt vmcnt(5)
	v_lshlrev_b32_e32 v87, 16, v55
	v_lshlrev_b32_e32 v86, 16, v54
	v_and_b32_e32 v55, 0xffff0000, v55
	v_and_b32_e32 v54, 0xffff0000, v54
	v_pk_fma_f32 v[104:105], v[84:85], v[84:85], v[104:105]
	v_add_f32_e32 v94, v103, v94
	v_pk_mul_f32 v[106:107], v[54:55], v[54:55]
	v_add_f32_e32 v94, v104, v94
	v_lshlrev_b32_e32 v89, 16, v57
	v_lshlrev_b32_e32 v88, 16, v56
	v_and_b32_e32 v57, 0xffff0000, v57
	v_and_b32_e32 v56, 0xffff0000, v56
	v_pk_fma_f32 v[106:107], v[86:87], v[86:87], v[106:107]
	v_add_f32_e32 v94, v105, v94
	v_pk_mul_f32 v[108:109], v[56:57], v[56:57]
	v_add_f32_e32 v94, v106, v94
	s_waitcnt vmcnt(4)
	v_lshlrev_b32_e32 v91, 16, v59
	v_lshlrev_b32_e32 v90, 16, v58
	v_and_b32_e32 v59, 0xffff0000, v59
	v_and_b32_e32 v58, 0xffff0000, v58
	v_pk_fma_f32 v[108:109], v[88:89], v[88:89], v[108:109]
	v_add_f32_e32 v94, v107, v94
	v_pk_mul_f32 v[110:111], v[58:59], v[58:59]
	v_add_f32_e32 v94, v108, v94
	v_lshlrev_b32_e32 v93, 16, v61
	v_lshlrev_b32_e32 v92, 16, v60
	v_and_b32_e32 v61, 0xffff0000, v61
	v_and_b32_e32 v60, 0xffff0000, v60
	v_pk_fma_f32 v[110:111], v[90:91], v[90:91], v[110:111]
	v_add_f32_e32 v94, v109, v94
	v_pk_mul_f32 v[112:113], v[60:61], v[60:61]
	v_add_f32_e32 v94, v110, v94
	v_pk_fma_f32 v[112:113], v[92:93], v[92:93], v[112:113]
	v_add_f32_e32 v94, v111, v94
	v_add_f32_e32 v94, v112, v94
	v_add_f32_e32 v94, v113, v94
	s_waitcnt lgkmcnt(0)
	s_nop 1
	v_add_f32_dpp v98, v94, v94 quad_perm:[1,0,3,2] row_mask:0xf bank_mask:0xf
	s_waitcnt lgkmcnt(0)
	s_nop 1
	v_add_f32_dpp v102, v98, v98 quad_perm:[2,3,0,1] row_mask:0xf bank_mask:0xf
	s_waitcnt vmcnt(3)
	v_lshlrev_b32_e32 v97, 16, v63
	v_lshlrev_b32_e32 v96, 16, v62
	v_and_b32_e32 v63, 0xffff0000, v63
	s_waitcnt lgkmcnt(0)
	s_nop 1
	v_add_f32_dpp v104, v102, v102 row_half_mirror row_mask:0xf bank_mask:0xf
	v_and_b32_e32 v62, 0xffff0000, v62
	v_lshlrev_b32_e32 v101, 16, v65
	v_lshlrev_b32_e32 v100, 16, v64
	v_and_b32_e32 v65, 0xffff0000, v65
	s_waitcnt lgkmcnt(0)
	s_nop 1
	v_add_f32_dpp v106, v104, v104 row_mirror row_mask:0xf bank_mask:0xf
	v_and_b32_e32 v64, 0xffff0000, v64
	s_waitcnt vmcnt(0)
	v_lshlrev_b32_e32 v109, 16, v77
	v_and_b32_e32 v77, 0xffff0000, v77
	v_lshlrev_b32_e32 v95, 16, v67
	s_waitcnt lgkmcnt(0)
	v_mov_b32_e32 v108, v106
	s_nop 1
	v_permlane16_swap_b32_e32 v108, v106
	v_add_f32_e32 v108, v108, v106
	v_lshlrev_b32_e32 v94, 16, v66
	v_and_b32_e32 v67, 0xffff0000, v67
	v_and_b32_e32 v66, 0xffff0000, v66
	v_lshlrev_b32_e32 v99, 16, v69
	s_waitcnt lgkmcnt(0)
; __device__ __forceinline__ unsigned pk2(float lo, float hi) { return f2bf(lo) | (f2bf(hi) << 16); }
; __device__ __forceinline__ void postnorm(const Ctx& c, const bf16* MF, bf16* XB, float* RS, const float* gpost, float* OUT) {
;     ...
;         const float rs = rsqrtf(wave_sum(s) * (1.f / DM) + EPS);
;         float s2 = 0.f;
; #pragma unroll
;         for (int j = 0; j < 4; ++j) { const float* gp = gpost + (c.lane + 64 * j) * 8; const f32x4 g0 = *(CF4)gp, g1 = *(CF4)(gp + 4);
; #pragma unroll
;             for (int k = 0; k < 4; ++k) { const float ga = (k < 2) ? g0[2 * k] : g1[2 * k - 4], gb = (k < 2) ? g0[2 * k + 1] : g1[2 * k - 3];
;                 v[j][2 * k] = bflo(xv[j][k]) + v[j][2 * k] * rs * ga; v[j][2 * k + 1] = bfhi(xv[j][k]) + v[j][2 * k + 1] * rs * gb;
;                 s2 += v[j][2 * k] * v[j][2 * k] + v[j][2 * k + 1] * v[j][2 * k + 1]; } }
;         if (OUT) {
; #pragma unroll
;             for (int j = 0; j < 4; ++j) { float* op = OUT + (size_t)row * DM + (c.lane + 64 * j) * 8; *(f32x4*)op = (f32x4){v[j][0], v[j][1], v[j][2], v[j][3]}; *(f32x4*)(op + 4) = (f32x4){v[j][4], v[j][5], v[j][6], v[j][7]}; }
;         } else {
; #pragma unroll
;             for (int j = 0; j < 4; ++j) { v4u o; o.x = pk2(v[j][0], v[j][1]); o.y = pk2(v[j][2], v[j][3]); o.z = pk2(v[j][4], v[j][5]); o.w = pk2(v[j][6], v[j][7]); xr[64 * j] = o; }
;             const float rs2 = rsqrtf(wave_sum(s2) * (1.f / DM) + EPS); if (c.lane == 0) RS[row] = rs2;
	v_mov_b32_e32 v110, v108
	s_nop 1
	v_permlane32_swap_b32_e32 v108, v110
	v_add_f32_e32 v108, v108, v110
	v_fmamk_f32 v108, v108, 0x3a000000, v45
	v_mul_f32_e32 v110, 0x4b800000, v108
	v_cmp_gt_f32_e32 vcc, s17, v108
	v_lshlrev_b32_e32 v98, 16, v68
	v_and_b32_e32 v69, 0xffff0000, v69
	v_cndmask_b32_e32 v108, v108, v110, vcc
	v_rsq_f32_e32 v110, v108
	v_lshlrev_b32_e32 v108, 16, v76
	v_and_b32_e32 v76, 0xffff0000, v76
	v_and_b32_e32 v68, 0xffff0000, v68
	v_mul_f32_e32 v111, 0x45800000, v110
	v_cndmask_b32_e32 v110, v110, v111, vcc
	v_pk_mul_f32 v[46:47], v[110:111], v[46:47] op_sel_hi:[0,1]
	v_pk_mul_f32 v[78:79], v[110:111], v[78:79] op_sel_hi:[0,1]
	v_pk_mul_f32 v[48:49], v[110:111], v[48:49] op_sel_hi:[0,1]
	v_pk_fma_f32 v[46:47], v[36:37], v[46:47], v[62:63]
	v_pk_mul_f32 v[60:61], v[110:111], v[60:61] op_sel_hi:[0,1]
	v_pk_mul_f32 v[80:81], v[110:111], v[80:81] op_sel_hi:[0,1]
	v_pk_fma_f32 v[78:79], v[8:9], v[78:79], v[96:97]
	v_pk_fma_f32 v[48:49], v[10:11], v[48:49], v[64:65]
	v_pk_fma_f32 v[60:61], v[34:35], v[60:61], v[76:77]
	v_pk_mul_f32 v[76:77], v[46:47], v[46:47]
	v_pk_mul_f32 v[50:51], v[110:111], v[50:51] op_sel_hi:[0,1]
	v_pk_fma_f32 v[62:63], v[4:5], v[80:81], v[100:101]
	v_pk_fma_f32 v[76:77], v[78:79], v[78:79], v[76:77]
	v_pk_mul_f32 v[80:81], v[48:49], v[48:49]
	v_pk_mul_f32 v[82:83], v[110:111], v[82:83] op_sel_hi:[0,1]
	v_pk_fma_f32 v[50:51], v[6:7], v[50:51], v[66:67]
	v_pk_fma_f32 v[80:81], v[62:63], v[62:63], v[80:81]
	v_add_f32_e32 v76, v76, v77
	v_pk_fma_f32 v[64:65], v[16:17], v[82:83], v[94:95]
	v_pk_mul_f32 v[82:83], v[50:51], v[50:51]
	v_add_f32_e32 v76, v80, v76
	v_pk_fma_f32 v[82:83], v[64:65], v[64:65], v[82:83]
	v_add_f32_e32 v76, v81, v76
	v_add_f32_e32 v76, v82, v76
	s_nop 2
	v_bfe_u32 v82, v46, 16, 1
	v_pk_mul_f32 v[52:53], v[110:111], v[52:53] op_sel_hi:[0,1]
	v_add3_u32 v46, v46, v82, s18
	s_nop 2
	v_bfe_u32 v77, v78, 16, 1
	s_nop 2
	v_pk_mul_f32 v[84:85], v[110:111], v[84:85] op_sel_hi:[0,1]
	v_pk_fma_f32 v[52:53], v[18:19], v[52:53], v[68:69]
	s_nop 2
	v_add3_u32 v77, v78, v77, s18
	v_lshlrev_b32_e32 v103, 16, v71
	v_lshlrev_b32_e32 v102, 16, v70
	v_and_b32_e32 v71, 0xffff0000, v71
	v_and_b32_e32 v70, 0xffff0000, v70
	v_pk_fma_f32 v[66:67], v[12:13], v[84:85], v[98:99]
	v_pk_mul_f32 v[54:55], v[110:111], v[54:55] op_sel_hi:[0,1]
	v_pk_mul_f32 v[84:85], v[52:53], v[52:53]
	v_lshrrev_b32_e32 v77, 16, v77
	s_nop 2
	v_pk_mul_f32 v[68:69], v[110:111], v[86:87] op_sel_hi:[0,1]
	v_pk_fma_f32 v[54:55], v[14:15], v[54:55], v[70:71]
	v_pk_fma_f32 v[84:85], v[66:67], v[66:67], v[84:85]
	v_add_f32_e32 v76, v83, v76
	v_cvt_pk_bf16_f32 v49, v63, v49
	v_cvt_pk_bf16_f32 v48, v62, v48
	v_cvt_pk_bf16_f32 v47, v79, v47
	v_and_or_b32 v46, v46, s16, v77
	v_lshlrev_b32_e32 v105, 16, v73
	v_lshlrev_b32_e32 v104, 16, v72
	v_and_b32_e32 v73, 0xffff0000, v73
	v_and_b32_e32 v72, 0xffff0000, v72
	v_pk_fma_f32 v[68:69], v[24:25], v[68:69], v[102:103]
	v_pk_mul_f32 v[56:57], v[110:111], v[56:57] op_sel_hi:[0,1]
	v_pk_mul_f32 v[86:87], v[54:55], v[54:55]
	v_add_f32_e32 v76, v84, v76
	global_store_dwordx4 v[38:39], v[46:49], off
	v_pk_mul_f32 v[70:71], v[110:111], v[88:89] op_sel_hi:[0,1]
	v_pk_fma_f32 v[56:57], v[26:27], v[56:57], v[72:73]
	s_nop 3
	v_pk_fma_f32 v[86:87], v[68:69], v[68:69], v[86:87]
	v_add_f32_e32 v76, v85, v76
	s_nop 7
	v_lshlrev_b32_e32 v107, 16, v75
	v_lshlrev_b32_e32 v106, 16, v74
	v_and_b32_e32 v75, 0xffff0000, v75
	v_and_b32_e32 v74, 0xffff0000, v74
	v_pk_fma_f32 v[70:71], v[20:21], v[70:71], v[104:105]
	v_pk_mul_f32 v[58:59], v[110:111], v[58:59] op_sel_hi:[0,1]
	v_pk_mul_f32 v[88:89], v[56:57], v[56:57]
	v_add_f32_e32 v76, v86, v76
	s_nop 3
	v_pk_mul_f32 v[72:73], v[110:111], v[90:91] op_sel_hi:[0,1]
	v_pk_fma_f32 v[58:59], v[22:23], v[58:59], v[74:75]
	v_pk_fma_f32 v[88:89], v[70:71], v[70:71], v[88:89]
	v_add_f32_e32 v76, v87, v76
	s_nop 3
	v_pk_fma_f32 v[72:73], v[32:33], v[72:73], v[106:107]
	v_pk_mul_f32 v[90:91], v[58:59], v[58:59]
	v_add_f32_e32 v76, v88, v76
	v_cvt_pk_bf16_f32 v49, v67, v53
	v_cvt_pk_bf16_f32 v48, v66, v52
	v_cvt_pk_bf16_f32 v47, v65, v51
	v_cvt_pk_bf16_f32 v46, v64, v50
	v_pk_mul_f32 v[74:75], v[110:111], v[92:93] op_sel_hi:[0,1]
	v_pk_fma_f32 v[90:91], v[72:73], v[72:73], v[90:91]
	v_add_f32_e32 v76, v89, v76
	global_store_dwordx4 v[38:39], v[46:49], off offset:1024
	v_pk_fma_f32 v[74:75], v[28:29], v[74:75], v[108:109]
	v_pk_mul_f32 v[92:93], v[60:61], v[60:61]
	s_nop 1
	v_add_f32_e32 v76, v90, v76
	s_nop 5
	v_pk_fma_f32 v[92:93], v[74:75], v[74:75], v[92:93]
	v_add_f32_e32 v76, v91, v76
	s_nop 5
	v_add_f32_e32 v76, v92, v76
	s_nop 5
	v_add_f32_e32 v76, v93, v76
	v_cvt_pk_bf16_f32 v49, v71, v57
	v_cvt_pk_bf16_f32 v48, v70, v56
	v_cvt_pk_bf16_f32 v47, v69, v55
	v_cvt_pk_bf16_f32 v46, v68, v54
	global_store_dwordx4 v[38:39], v[46:49], off offset:2048
	s_nop 3
	s_waitcnt lgkmcnt(0)
	s_nop 1
	v_add_f32_dpp v47, v76, v76 quad_perm:[1,0,3,2] row_mask:0xf bank_mask:0xf
	s_nop 3
	s_waitcnt lgkmcnt(0)
	s_nop 1
	v_add_f32_dpp v47, v47, v47 quad_perm:[2,3,0,1] row_mask:0xf bank_mask:0xf
	s_nop 1
	v_cvt_pk_bf16_f32 v51, v75, v61
	s_nop 0
	s_waitcnt lgkmcnt(0)
	s_nop 1
	v_add_f32_dpp v47, v47, v47 row_half_mirror row_mask:0xf bank_mask:0xf
	s_nop 3
	s_waitcnt lgkmcnt(0)
	s_nop 1
	v_add_f32_dpp v47, v47, v47 row_mirror row_mask:0xf bank_mask:0xf
	s_nop 3
	s_waitcnt lgkmcnt(0)
	v_mov_b32_e32 v50, v47
	v_mov_b32_e32 v46, v47
	s_nop 1
	v_permlane16_swap_b32_e32 v46, v50
	v_add_f32_e32 v46, v46, v50
	ds_bpermute_b32 v47, v44, v46
	s_nop 0
	v_cvt_pk_bf16_f32 v50, v74, v60
	v_cvt_pk_bf16_f32 v49, v73, v59
	v_cvt_pk_bf16_f32 v48, v72, v58
	global_store_dwordx4 v[38:39], v[48:51], off offset:3072
	s_and_saveexec_b64 s[12:13], s[0:1]
	s_cbranch_execz .LBB0_2483
	s_waitcnt lgkmcnt(0)
	v_add_f32_e32 v38, v46, v47
	v_fmamk_f32 v38, v38, 0x3a000000, v45
	v_mul_f32_e32 v39, 0x4b800000, v38
	v_cmp_gt_f32_e32 vcc, s17, v38
	v_readlane_b32 s20, v253, 0
	v_readlane_b32 s21, v253, 1
	v_cndmask_b32_e32 v38, v38, v39, vcc
	v_rsq_f32_e32 v38, v38
	s_add_u32 s20, s20, s14
	s_addc_u32 s21, s21, s15
	v_mul_f32_e32 v39, 0x45800000, v38
	v_cndmask_b32_e32 v38, v38, v39, vcc
	global_store_dword v251, v38, s[20:21]
	s_branch .LBB0_2483

; __device__ __forceinline__ float wave_sum(float v) {
; #pragma unroll
;     for (int o = 1; o < 64; o <<= 1) v += __shfl_xor(v, o);
;     return v;
; __device__ __forceinline__ void postnorm(const Ctx& c, const bf16* MF, bf16* XB, float* RS, const float* gpost, float* OUT) {
;     ...
;         const v4u* mr = (const v4u*)(MF + (size_t)row * DM) + c.lane; v4u* xr = (v4u*)(XB + (size_t)row * DM) + c.lane;
;         v4u mv[4], xv[4]; float v[4][8]; float s = 0.f;
; #pragma unroll
;         for (int j = 0; j < 4; ++j) { mv[j] = mr[64 * j]; xv[j] = xr[64 * j]; }
; #pragma unroll
;         for (int j = 0; j < 4; ++j)
; #pragma unroll
;             for (int k = 0; k < 4; ++k) { v[j][2 * k] = bflo(mv[j][k]); v[j][2 * k + 1] = bfhi(mv[j][k]); s += v[j][2 * k] * v[j][2 * k] + v[j][2 * k + 1] * v[j][2 * k + 1]; }
;         const float rs = rsqrtf(wave_sum(s) * (1.f / DM) + EPS);
.LBB0_3204:
	v_readlane_b32 s10, v253, 0
	v_readlane_b32 s11, v253, 1
	s_nop 1
	v_lshl_add_u64 v[38:39], s[10:11], 0, v[30:31]
	v_add_co_u32_e32 v58, vcc, 0xd400000, v38
	s_nop 1
	v_addc_co_u32_e32 v59, vcc, 0, v39, vcc
	s_waitcnt lgkmcnt(0)
	global_load_dwordx4 v[46:49], v[58:59], off
	global_load_dwordx4 v[50:53], v[58:59], off offset:1024
	global_load_dwordx4 v[54:57], v[58:59], off offset:2048
	s_nop 0
	global_load_dwordx4 v[58:61], v[58:59], off offset:3072
	v_add_co_u32_e32 v38, vcc, 0x9400000, v38
	s_waitcnt vmcnt(3)
	v_lshlrev_b32_e32 v79, 16, v47
	v_addc_co_u32_e32 v39, vcc, 0, v39, vcc
	global_load_dwordx4 v[62:65], v[38:39], off
	global_load_dwordx4 v[66:69], v[38:39], off offset:1024
	global_load_dwordx4 v[70:73], v[38:39], off offset:2048
	global_load_dwordx4 v[74:77], v[38:39], off offset:3072
	v_lshlrev_b32_e32 v78, 16, v46
	v_and_b32_e32 v47, 0xffff0000, v47
	v_and_b32_e32 v46, 0xffff0000, v46
	v_lshlrev_b32_e32 v81, 16, v49
	v_lshlrev_b32_e32 v80, 16, v48
	v_and_b32_e32 v49, 0xffff0000, v49
	v_and_b32_e32 v48, 0xffff0000, v48
	v_pk_mul_f32 v[94:95], v[46:47], v[46:47]
	v_pk_mul_f32 v[98:99], v[48:49], v[48:49]
	v_pk_fma_f32 v[94:95], v[78:79], v[78:79], v[94:95]
	s_waitcnt vmcnt(6)
	v_lshlrev_b32_e32 v83, 16, v51
	v_lshlrev_b32_e32 v82, 16, v50
	v_and_b32_e32 v51, 0xffff0000, v51
	v_and_b32_e32 v50, 0xffff0000, v50
	v_pk_fma_f32 v[98:99], v[80:81], v[80:81], v[98:99]
	v_add_f32_e32 v94, v94, v95
	v_pk_mul_f32 v[102:103], v[50:51], v[50:51]
	v_add_f32_e32 v94, v98, v94
	v_lshlrev_b32_e32 v85, 16, v53
	v_lshlrev_b32_e32 v84, 16, v52
	v_and_b32_e32 v53, 0xffff0000, v53
	v_and_b32_e32 v52, 0xffff0000, v52
	v_pk_fma_f32 v[102:103], v[82:83], v[82:83], v[102:103]
	v_add_f32_e32 v94, v99, v94
	v_pk_mul_f32 v[104:105], v[52:53], v[52:53]
	v_add_f32_e32 v94, v102, v94
	s_waitcnt vmcnt(5)
	v_lshlrev_b32_e32 v87, 16, v55
	v_lshlrev_b32_e32 v86, 16, v54
	v_and_b32_e32 v55, 0xffff0000, v55
	v_and_b32_e32 v54, 0xffff0000, v54
	v_pk_fma_f32 v[104:105], v[84:85], v[84:85], v[104:105]
	v_add_f32_e32 v94, v103, v94
	v_pk_mul_f32 v[106:107], v[54:55], v[54:55]
	v_add_f32_e32 v94, v104, v94
	v_lshlrev_b32_e32 v89, 16, v57
	v_lshlrev_b32_e32 v88, 16, v56
	v_and_b32_e32 v57, 0xffff0000, v57
	v_and_b32_e32 v56, 0xffff0000, v56
	v_pk_fma_f32 v[106:107], v[86:87], v[86:87], v[106:107]
	v_add_f32_e32 v94, v105, v94
	v_pk_mul_f32 v[108:109], v[56:57], v[56:57]
	v_add_f32_e32 v94, v106, v94
	s_waitcnt vmcnt(4)
	v_lshlrev_b32_e32 v91, 16, v59
	v_lshlrev_b32_e32 v90, 16, v58
	v_and_b32_e32 v59, 0xffff0000, v59
	v_and_b32_e32 v58, 0xffff0000, v58
	v_pk_fma_f32 v[108:109], v[88:89], v[88:89], v[108:109]
	v_add_f32_e32 v94, v107, v94
	v_pk_mul_f32 v[110:111], v[58:59], v[58:59]
	v_add_f32_e32 v94, v108, v94
	v_lshlrev_b32_e32 v93, 16, v61
	v_lshlrev_b32_e32 v92, 16, v60
	v_and_b32_e32 v61, 0xffff0000, v61
	v_and_b32_e32 v60, 0xffff0000, v60
	v_pk_fma_f32 v[110:111], v[90:91], v[90:91], v[110:111]
	v_add_f32_e32 v94, v109, v94
	v_pk_mul_f32 v[112:113], v[60:61], v[60:61]
	v_add_f32_e32 v94, v110, v94
	v_pk_fma_f32 v[112:113], v[92:93], v[92:93], v[112:113]
	v_add_f32_e32 v94, v111, v94
	v_add_f32_e32 v94, v112, v94
	v_add_f32_e32 v94, v113, v94
	s_waitcnt lgkmcnt(0)
	s_nop 1
	v_add_f32_dpp v98, v94, v94 quad_perm:[1,0,3,2] row_mask:0xf bank_mask:0xf
	s_waitcnt lgkmcnt(0)
	s_nop 1
	v_add_f32_dpp v102, v98, v98 quad_perm:[2,3,0,1] row_mask:0xf bank_mask:0xf
	s_waitcnt vmcnt(3)
	v_lshlrev_b32_e32 v97, 16, v63
	v_lshlrev_b32_e32 v96, 16, v62
	v_and_b32_e32 v63, 0xffff0000, v63
	s_waitcnt lgkmcnt(0)
	s_nop 1
	v_add_f32_dpp v104, v102, v102 row_half_mirror row_mask:0xf bank_mask:0xf
	v_and_b32_e32 v62, 0xffff0000, v62
	v_lshlrev_b32_e32 v101, 16, v65
	v_lshlrev_b32_e32 v100, 16, v64
	v_and_b32_e32 v65, 0xffff0000, v65
	s_waitcnt lgkmcnt(0)
	s_nop 1
	v_add_f32_dpp v106, v104, v104 row_mirror row_mask:0xf bank_mask:0xf
	v_and_b32_e32 v64, 0xffff0000, v64
	s_waitcnt vmcnt(0)
	v_lshlrev_b32_e32 v109, 16, v77
	v_and_b32_e32 v77, 0xffff0000, v77
	v_lshlrev_b32_e32 v95, 16, v67
	s_waitcnt lgkmcnt(0)
	v_mov_b32_e32 v108, v106
	s_nop 1
	v_permlane16_swap_b32_e32 v108, v106
	v_add_f32_e32 v108, v108, v106
	v_lshlrev_b32_e32 v94, 16, v66
	v_and_b32_e32 v67, 0xffff0000, v67
	v_and_b32_e32 v66, 0xffff0000, v66
	v_lshlrev_b32_e32 v99, 16, v69
	s_waitcnt lgkmcnt(0)
; __device__ __forceinline__ unsigned pk2(float lo, float hi) { return f2bf(lo) | (f2bf(hi) << 16); }
; __device__ __forceinline__ void postnorm(const Ctx& c, const bf16* MF, bf16* XB, float* RS, const float* gpost, float* OUT) {
;     ...
;         const float rs = rsqrtf(wave_sum(s) * (1.f / DM) + EPS);
;         float s2 = 0.f;
; #pragma unroll
;         for (int j = 0; j < 4; ++j) { const float* gp = gpost + (c.lane + 64 * j) * 8; const f32x4 g0 = *(CF4)gp, g1 = *(CF4)(gp + 4);
; #pragma unroll
;             for (int k = 0; k < 4; ++k) { const float ga = (k < 2) ? g0[2 * k] : g1[2 * k - 4], gb = (k < 2) ? g0[2 * k + 1] : g1[2 * k - 3];
;                 v[j][2 * k] = bflo(xv[j][k]) + v[j][2 * k] * rs * ga; v[j][2 * k + 1] = bfhi(xv[j][k]) + v[j][2 * k + 1] * rs * gb;
;                 s2 += v[j][2 * k] * v[j][2 * k] + v[j][2 * k + 1] * v[j][2 * k + 1]; } }
;         if (OUT) {
; #pragma unroll
;             for (int j = 0; j < 4; ++j) { float* op = OUT + (size_t)row * DM + (c.lane + 64 * j) * 8; *(f32x4*)op = (f32x4){v[j][0], v[j][1], v[j][2], v[j][3]}; *(f32x4*)(op + 4) = (f32x4){v[j][4], v[j][5], v[j][6], v[j][7]}; }
;         } else {
; #pragma unroll
;             for (int j = 0; j < 4; ++j) { v4u o; o.x = pk2(v[j][0], v[j][1]); o.y = pk2(v[j][2], v[j][3]); o.z = pk2(v[j][4], v[j][5]); o.w = pk2(v[j][6], v[j][7]); xr[64 * j] = o; }
;             const float rs2 = rsqrtf(wave_sum(s2) * (1.f / DM) + EPS); if (c.lane == 0) RS[row] = rs2;
	v_mov_b32_e32 v110, v108
	s_nop 1
	v_permlane32_swap_b32_e32 v108, v110
	v_add_f32_e32 v108, v108, v110
	v_fmamk_f32 v108, v108, 0x3a000000, v45
	v_mul_f32_e32 v110, 0x4b800000, v108
	v_cmp_gt_f32_e32 vcc, s15, v108
	v_lshlrev_b32_e32 v98, 16, v68
	v_and_b32_e32 v69, 0xffff0000, v69
	v_cndmask_b32_e32 v108, v108, v110, vcc
	v_rsq_f32_e32 v110, v108
	v_lshlrev_b32_e32 v108, 16, v76
	v_and_b32_e32 v76, 0xffff0000, v76
	v_and_b32_e32 v68, 0xffff0000, v68
	v_mul_f32_e32 v111, 0x45800000, v110
	v_cndmask_b32_e32 v110, v110, v111, vcc
	v_pk_mul_f32 v[46:47], v[110:111], v[46:47] op_sel_hi:[0,1]
	v_pk_mul_f32 v[78:79], v[110:111], v[78:79] op_sel_hi:[0,1]
	v_pk_mul_f32 v[48:49], v[110:111], v[48:49] op_sel_hi:[0,1]
	v_pk_fma_f32 v[46:47], v[36:37], v[46:47], v[62:63]
	v_pk_mul_f32 v[60:61], v[110:111], v[60:61] op_sel_hi:[0,1]
	v_pk_mul_f32 v[80:81], v[110:111], v[80:81] op_sel_hi:[0,1]
	v_pk_fma_f32 v[78:79], v[8:9], v[78:79], v[96:97]
	v_pk_fma_f32 v[48:49], v[10:11], v[48:49], v[64:65]
	v_pk_fma_f32 v[60:61], v[34:35], v[60:61], v[76:77]
	v_pk_mul_f32 v[76:77], v[46:47], v[46:47]
	v_pk_mul_f32 v[50:51], v[110:111], v[50:51] op_sel_hi:[0,1]
	v_pk_fma_f32 v[62:63], v[4:5], v[80:81], v[100:101]
	v_pk_fma_f32 v[76:77], v[78:79], v[78:79], v[76:77]
	v_pk_mul_f32 v[80:81], v[48:49], v[48:49]
	v_pk_mul_f32 v[82:83], v[110:111], v[82:83] op_sel_hi:[0,1]
	v_pk_fma_f32 v[50:51], v[6:7], v[50:51], v[66:67]
	v_pk_fma_f32 v[80:81], v[62:63], v[62:63], v[80:81]
	v_add_f32_e32 v76, v76, v77
	v_pk_fma_f32 v[64:65], v[16:17], v[82:83], v[94:95]
	v_pk_mul_f32 v[82:83], v[50:51], v[50:51]
	v_add_f32_e32 v76, v80, v76
	v_pk_fma_f32 v[82:83], v[64:65], v[64:65], v[82:83]
	v_add_f32_e32 v76, v81, v76
	v_add_f32_e32 v76, v82, v76
	s_nop 2
	v_bfe_u32 v82, v46, 16, 1
	v_pk_mul_f32 v[52:53], v[110:111], v[52:53] op_sel_hi:[0,1]
	v_add3_u32 v46, v46, v82, s16
	s_nop 2
	v_bfe_u32 v77, v78, 16, 1
	s_nop 2
	v_pk_mul_f32 v[84:85], v[110:111], v[84:85] op_sel_hi:[0,1]
	v_pk_fma_f32 v[52:53], v[18:19], v[52:53], v[68:69]
	s_nop 2
	v_add3_u32 v77, v78, v77, s16
	v_lshlrev_b32_e32 v103, 16, v71
	v_lshlrev_b32_e32 v102, 16, v70
	v_and_b32_e32 v71, 0xffff0000, v71
	v_and_b32_e32 v70, 0xffff0000, v70
	v_pk_fma_f32 v[66:67], v[12:13], v[84:85], v[98:99]
	v_pk_mul_f32 v[54:55], v[110:111], v[54:55] op_sel_hi:[0,1]
	v_pk_mul_f32 v[84:85], v[52:53], v[52:53]
	v_lshrrev_b32_e32 v77, 16, v77
	s_nop 2
	v_pk_mul_f32 v[68:69], v[110:111], v[86:87] op_sel_hi:[0,1]
	v_pk_fma_f32 v[54:55], v[14:15], v[54:55], v[70:71]
	v_pk_fma_f32 v[84:85], v[66:67], v[66:67], v[84:85]
	v_add_f32_e32 v76, v83, v76
	v_cvt_pk_bf16_f32 v49, v63, v49
	v_cvt_pk_bf16_f32 v48, v62, v48
	v_cvt_pk_bf16_f32 v47, v79, v47
	v_and_or_b32 v46, v46, s14, v77
	v_lshlrev_b32_e32 v105, 16, v73
	v_lshlrev_b32_e32 v104, 16, v72
	v_and_b32_e32 v73, 0xffff0000, v73
	v_and_b32_e32 v72, 0xffff0000, v72
	v_pk_fma_f32 v[68:69], v[24:25], v[68:69], v[102:103]
	v_pk_mul_f32 v[56:57], v[110:111], v[56:57] op_sel_hi:[0,1]
	v_pk_mul_f32 v[86:87], v[54:55], v[54:55]
	v_add_f32_e32 v76, v84, v76
	global_store_dwordx4 v[38:39], v[46:49], off
	v_pk_mul_f32 v[70:71], v[110:111], v[88:89] op_sel_hi:[0,1]
	v_pk_fma_f32 v[56:57], v[26:27], v[56:57], v[72:73]
	s_nop 3
	v_pk_fma_f32 v[86:87], v[68:69], v[68:69], v[86:87]
	v_add_f32_e32 v76, v85, v76
	s_nop 7
	v_lshlrev_b32_e32 v107, 16, v75
	v_lshlrev_b32_e32 v106, 16, v74
	v_and_b32_e32 v75, 0xffff0000, v75
	v_and_b32_e32 v74, 0xffff0000, v74
	v_pk_fma_f32 v[70:71], v[20:21], v[70:71], v[104:105]
	v_pk_mul_f32 v[58:59], v[110:111], v[58:59] op_sel_hi:[0,1]
	v_pk_mul_f32 v[88:89], v[56:57], v[56:57]
	v_add_f32_e32 v76, v86, v76
	s_nop 3
	v_pk_mul_f32 v[72:73], v[110:111], v[90:91] op_sel_hi:[0,1]
	v_pk_fma_f32 v[58:59], v[22:23], v[58:59], v[74:75]
	v_pk_fma_f32 v[88:89], v[70:71], v[70:71], v[88:89]
	v_add_f32_e32 v76, v87, v76
	s_nop 3
	v_pk_fma_f32 v[72:73], v[32:33], v[72:73], v[106:107]
	v_pk_mul_f32 v[90:91], v[58:59], v[58:59]
	v_add_f32_e32 v76, v88, v76
	v_cvt_pk_bf16_f32 v49, v67, v53
	v_cvt_pk_bf16_f32 v48, v66, v52
	v_cvt_pk_bf16_f32 v47, v65, v51
	v_cvt_pk_bf16_f32 v46, v64, v50
	v_pk_mul_f32 v[74:75], v[110:111], v[92:93] op_sel_hi:[0,1]
	v_pk_fma_f32 v[90:91], v[72:73], v[72:73], v[90:91]
	v_add_f32_e32 v76, v89, v76
	global_store_dwordx4 v[38:39], v[46:49], off offset:1024
	v_pk_fma_f32 v[74:75], v[28:29], v[74:75], v[108:109]
	v_pk_mul_f32 v[92:93], v[60:61], v[60:61]
	s_nop 1
	v_add_f32_e32 v76, v90, v76
	s_nop 5
	v_pk_fma_f32 v[92:93], v[74:75], v[74:75], v[92:93]
	v_add_f32_e32 v76, v91, v76
	s_nop 5
	v_add_f32_e32 v76, v92, v76
	s_nop 5
	v_add_f32_e32 v76, v93, v76
	v_cvt_pk_bf16_f32 v49, v71, v57
	v_cvt_pk_bf16_f32 v48, v70, v56
	v_cvt_pk_bf16_f32 v47, v69, v55
	v_cvt_pk_bf16_f32 v46, v68, v54
	global_store_dwordx4 v[38:39], v[46:49], off offset:2048
	s_nop 3
	s_waitcnt lgkmcnt(0)
	s_nop 1
	v_add_f32_dpp v47, v76, v76 quad_perm:[1,0,3,2] row_mask:0xf bank_mask:0xf
	s_nop 3
	s_waitcnt lgkmcnt(0)
	s_nop 1
	v_add_f32_dpp v47, v47, v47 quad_perm:[2,3,0,1] row_mask:0xf bank_mask:0xf
	s_nop 1
	v_cvt_pk_bf16_f32 v51, v75, v61
	s_nop 0
	s_waitcnt lgkmcnt(0)
	s_nop 1
	v_add_f32_dpp v47, v47, v47 row_half_mirror row_mask:0xf bank_mask:0xf
	s_nop 3
	s_waitcnt lgkmcnt(0)
	s_nop 1
	v_add_f32_dpp v47, v47, v47 row_mirror row_mask:0xf bank_mask:0xf
	s_nop 3
	s_waitcnt lgkmcnt(0)
	v_mov_b32_e32 v50, v47
	v_mov_b32_e32 v46, v47
	s_nop 1
	v_permlane16_swap_b32_e32 v46, v50
	v_add_f32_e32 v46, v46, v50
	ds_bpermute_b32 v47, v44, v46
	s_nop 0
	v_cvt_pk_bf16_f32 v50, v74, v60
	v_cvt_pk_bf16_f32 v49, v73, v59
	v_cvt_pk_bf16_f32 v48, v72, v58
	global_store_dwordx4 v[38:39], v[48:51], off offset:3072
	s_and_saveexec_b64 s[10:11], s[0:1]
	s_cbranch_execz .LBB0_3203
	s_waitcnt lgkmcnt(0)
	v_add_f32_e32 v38, v46, v47
	v_fmamk_f32 v38, v38, 0x3a000000, v45
	v_mul_f32_e32 v39, 0x4b800000, v38
	v_cmp_gt_f32_e32 vcc, s15, v38
	v_readlane_b32 s18, v253, 0
	v_readlane_b32 s19, v253, 1
	v_cndmask_b32_e32 v38, v38, v39, vcc
	v_rsq_f32_e32 v38, v38
	s_add_u32 s18, s18, s12
	s_addc_u32 s19, s19, s13
	v_mul_f32_e32 v39, 0x45800000, v38
	v_cndmask_b32_e32 v38, v38, v39, vcc
	global_store_dword v251, v38, s[18:19]
	s_branch .LBB0_3203

; __device__ __forceinline__ float wave_sum(float v) {
; #pragma unroll
;     for (int o = 1; o < 64; o <<= 1) v += __shfl_xor(v, o);
;     return v;
; __device__ __forceinline__ void postnorm(const Ctx& c, const bf16* MF, bf16* XB, float* RS, const float* gpost, float* OUT) {
;     ...
;         const v4u* mr = (const v4u*)(MF + (size_t)row * DM) + c.lane; v4u* xr = (v4u*)(XB + (size_t)row * DM) + c.lane;
;         v4u mv[4], xv[4]; float v[4][8]; float s = 0.f;
; #pragma unroll
;         for (int j = 0; j < 4; ++j) { mv[j] = mr[64 * j]; xv[j] = xr[64 * j]; }
; #pragma unroll
;         for (int j = 0; j < 4; ++j)
; #pragma unroll
;             for (int k = 0; k < 4; ++k) { v[j][2 * k] = bflo(mv[j][k]); v[j][2 * k + 1] = bfhi(mv[j][k]); s += v[j][2 * k] * v[j][2 * k] + v[j][2 * k + 1] * v[j][2 * k + 1]; }
;         const float rs = rsqrtf(wave_sum(s) * (1.f / DM) + EPS);
.LBB0_3812:
	v_readlane_b32 s10, v253, 0
	v_readlane_b32 s11, v253, 1
	s_nop 1
	v_lshl_add_u64 v[34:35], s[10:11], 0, v[36:37]
	v_add_co_u32_e32 v58, vcc, 0xd400000, v34
	s_nop 1
	v_addc_co_u32_e32 v59, vcc, 0, v35, vcc
	s_waitcnt lgkmcnt(0)
	global_load_dwordx4 v[46:49], v[58:59], off
	global_load_dwordx4 v[50:53], v[58:59], off offset:1024
	global_load_dwordx4 v[54:57], v[58:59], off offset:2048
	s_nop 0
	global_load_dwordx4 v[58:61], v[58:59], off offset:3072
	v_add_co_u32_e32 v34, vcc, 0x9400000, v34
	s_waitcnt vmcnt(3)
	v_lshlrev_b32_e32 v79, 16, v47
	v_addc_co_u32_e32 v35, vcc, 0, v35, vcc
	global_load_dwordx4 v[62:65], v[34:35], off
	global_load_dwordx4 v[66:69], v[34:35], off offset:1024
	global_load_dwordx4 v[70:73], v[34:35], off offset:2048
	global_load_dwordx4 v[74:77], v[34:35], off offset:3072
	v_lshlrev_b32_e32 v78, 16, v46
	v_and_b32_e32 v47, 0xffff0000, v47
	v_and_b32_e32 v46, 0xffff0000, v46
	v_lshlrev_b32_e32 v81, 16, v49
	v_lshlrev_b32_e32 v80, 16, v48
	v_and_b32_e32 v49, 0xffff0000, v49
	v_and_b32_e32 v48, 0xffff0000, v48
	v_pk_mul_f32 v[94:95], v[46:47], v[46:47]
	v_pk_mul_f32 v[98:99], v[48:49], v[48:49]
	v_pk_fma_f32 v[94:95], v[78:79], v[78:79], v[94:95]
	s_waitcnt vmcnt(6)
	v_lshlrev_b32_e32 v83, 16, v51
	v_lshlrev_b32_e32 v82, 16, v50
	v_and_b32_e32 v51, 0xffff0000, v51
	v_and_b32_e32 v50, 0xffff0000, v50
	v_pk_fma_f32 v[98:99], v[80:81], v[80:81], v[98:99]
	v_add_f32_e32 v94, v94, v95
	v_pk_mul_f32 v[102:103], v[50:51], v[50:51]
	v_add_f32_e32 v94, v98, v94
	v_lshlrev_b32_e32 v85, 16, v53
	v_lshlrev_b32_e32 v84, 16, v52
	v_and_b32_e32 v53, 0xffff0000, v53
	v_and_b32_e32 v52, 0xffff0000, v52
	v_pk_fma_f32 v[102:103], v[82:83], v[82:83], v[102:103]
	v_add_f32_e32 v94, v99, v94
	v_pk_mul_f32 v[104:105], v[52:53], v[52:53]
	v_add_f32_e32 v94, v102, v94
	s_waitcnt vmcnt(5)
	v_lshlrev_b32_e32 v87, 16, v55
	v_lshlrev_b32_e32 v86, 16, v54
	v_and_b32_e32 v55, 0xffff0000, v55
	v_and_b32_e32 v54, 0xffff0000, v54
	v_pk_fma_f32 v[104:105], v[84:85], v[84:85], v[104:105]
	v_add_f32_e32 v94, v103, v94
	v_pk_mul_f32 v[106:107], v[54:55], v[54:55]
	v_add_f32_e32 v94, v104, v94
	v_lshlrev_b32_e32 v89, 16, v57
	v_lshlrev_b32_e32 v88, 16, v56
	v_and_b32_e32 v57, 0xffff0000, v57
	v_and_b32_e32 v56, 0xffff0000, v56
	v_pk_fma_f32 v[106:107], v[86:87], v[86:87], v[106:107]
	v_add_f32_e32 v94, v105, v94
	v_pk_mul_f32 v[108:109], v[56:57], v[56:57]
	v_add_f32_e32 v94, v106, v94
	s_waitcnt vmcnt(4)
	v_lshlrev_b32_e32 v91, 16, v59
	v_lshlrev_b32_e32 v90, 16, v58
	v_and_b32_e32 v59, 0xffff0000, v59
	v_and_b32_e32 v58, 0xffff0000, v58
	v_pk_fma_f32 v[108:109], v[88:89], v[88:89], v[108:109]
	v_add_f32_e32 v94, v107, v94
	v_pk_mul_f32 v[110:111], v[58:59], v[58:59]
	v_add_f32_e32 v94, v108, v94
	v_lshlrev_b32_e32 v93, 16, v61
	v_lshlrev_b32_e32 v92, 16, v60
	v_and_b32_e32 v61, 0xffff0000, v61
	v_and_b32_e32 v60, 0xffff0000, v60
	v_pk_fma_f32 v[110:111], v[90:91], v[90:91], v[110:111]
	v_add_f32_e32 v94, v109, v94
	v_pk_mul_f32 v[112:113], v[60:61], v[60:61]
	v_add_f32_e32 v94, v110, v94
	v_pk_fma_f32 v[112:113], v[92:93], v[92:93], v[112:113]
	v_add_f32_e32 v94, v111, v94
	v_add_f32_e32 v94, v112, v94
	v_add_f32_e32 v94, v113, v94
	s_waitcnt lgkmcnt(0)
	s_nop 1
	v_add_f32_dpp v98, v94, v94 quad_perm:[1,0,3,2] row_mask:0xf bank_mask:0xf
	s_waitcnt lgkmcnt(0)
	s_nop 1
	v_add_f32_dpp v102, v98, v98 quad_perm:[2,3,0,1] row_mask:0xf bank_mask:0xf
	s_waitcnt vmcnt(3)
	v_lshlrev_b32_e32 v97, 16, v63
	v_lshlrev_b32_e32 v96, 16, v62
	v_and_b32_e32 v63, 0xffff0000, v63
	s_waitcnt lgkmcnt(0)
	s_nop 1
	v_add_f32_dpp v104, v102, v102 row_half_mirror row_mask:0xf bank_mask:0xf
	v_and_b32_e32 v62, 0xffff0000, v62
	v_lshlrev_b32_e32 v101, 16, v65
	v_lshlrev_b32_e32 v100, 16, v64
	v_and_b32_e32 v65, 0xffff0000, v65
	s_waitcnt lgkmcnt(0)
	s_nop 1
	v_add_f32_dpp v106, v104, v104 row_mirror row_mask:0xf bank_mask:0xf
	v_and_b32_e32 v64, 0xffff0000, v64
	s_waitcnt vmcnt(0)
	v_lshlrev_b32_e32 v109, 16, v77
	v_and_b32_e32 v77, 0xffff0000, v77
	v_lshlrev_b32_e32 v95, 16, v67
	s_waitcnt lgkmcnt(0)
	v_mov_b32_e32 v108, v106
	s_nop 1
	v_permlane16_swap_b32_e32 v108, v106
	v_add_f32_e32 v108, v108, v106
	v_lshlrev_b32_e32 v94, 16, v66
	v_and_b32_e32 v67, 0xffff0000, v67
	v_and_b32_e32 v66, 0xffff0000, v66
	v_lshlrev_b32_e32 v99, 16, v69
	s_waitcnt lgkmcnt(0)
; __device__ __forceinline__ unsigned pk2(float lo, float hi) { return f2bf(lo) | (f2bf(hi) << 16); }
; __device__ __forceinline__ void postnorm(const Ctx& c, const bf16* MF, bf16* XB, float* RS, const float* gpost, float* OUT) {
;     ...
;         const float rs = rsqrtf(wave_sum(s) * (1.f / DM) + EPS);
;         float s2 = 0.f;
; #pragma unroll
;         for (int j = 0; j < 4; ++j) { const float* gp = gpost + (c.lane + 64 * j) * 8; const f32x4 g0 = *(CF4)gp, g1 = *(CF4)(gp + 4);
; #pragma unroll
;             for (int k = 0; k < 4; ++k) { const float ga = (k < 2) ? g0[2 * k] : g1[2 * k - 4], gb = (k < 2) ? g0[2 * k + 1] : g1[2 * k - 3];
;                 v[j][2 * k] = bflo(xv[j][k]) + v[j][2 * k] * rs * ga; v[j][2 * k + 1] = bfhi(xv[j][k]) + v[j][2 * k + 1] * rs * gb;
;                 s2 += v[j][2 * k] * v[j][2 * k] + v[j][2 * k + 1] * v[j][2 * k + 1]; } }
;         if (OUT) {
; #pragma unroll
;             for (int j = 0; j < 4; ++j) { float* op = OUT + (size_t)row * DM + (c.lane + 64 * j) * 8; *(f32x4*)op = (f32x4){v[j][0], v[j][1], v[j][2], v[j][3]}; *(f32x4*)(op + 4) = (f32x4){v[j][4], v[j][5], v[j][6], v[j][7]}; }
;         } else {
; #pragma unroll
;             for (int j = 0; j < 4; ++j) { v4u o; o.x = pk2(v[j][0], v[j][1]); o.y = pk2(v[j][2], v[j][3]); o.z = pk2(v[j][4], v[j][5]); o.w = pk2(v[j][6], v[j][7]); xr[64 * j] = o; }
;             const float rs2 = rsqrtf(wave_sum(s2) * (1.f / DM) + EPS); if (c.lane == 0) RS[row] = rs2;
	v_mov_b32_e32 v110, v108
	s_nop 1
	v_permlane32_swap_b32_e32 v108, v110
	v_add_f32_e32 v108, v108, v110
	v_fmamk_f32 v108, v108, 0x3a000000, v3
	v_mul_f32_e32 v110, 0x4b800000, v108
	v_cmp_gt_f32_e32 vcc, s15, v108
	v_lshlrev_b32_e32 v98, 16, v68
	v_and_b32_e32 v69, 0xffff0000, v69
	v_cndmask_b32_e32 v108, v108, v110, vcc
	v_rsq_f32_e32 v110, v108
	v_lshlrev_b32_e32 v108, 16, v76
	v_and_b32_e32 v76, 0xffff0000, v76
	v_and_b32_e32 v68, 0xffff0000, v68
	v_mul_f32_e32 v111, 0x45800000, v110
	v_cndmask_b32_e32 v110, v110, v111, vcc
	v_pk_mul_f32 v[46:47], v[110:111], v[46:47] op_sel_hi:[0,1]
	v_pk_mul_f32 v[78:79], v[110:111], v[78:79] op_sel_hi:[0,1]
	v_pk_mul_f32 v[48:49], v[110:111], v[48:49] op_sel_hi:[0,1]
	v_pk_fma_f32 v[46:47], v[38:39], v[46:47], v[62:63]
	v_pk_mul_f32 v[60:61], v[110:111], v[60:61] op_sel_hi:[0,1]
	v_pk_mul_f32 v[80:81], v[110:111], v[80:81] op_sel_hi:[0,1]
	v_pk_fma_f32 v[78:79], v[4:5], v[78:79], v[96:97]
	v_pk_fma_f32 v[48:49], v[6:7], v[48:49], v[64:65]
	v_pk_fma_f32 v[60:61], v[30:31], v[60:61], v[76:77]
	v_pk_mul_f32 v[76:77], v[46:47], v[46:47]
	v_pk_mul_f32 v[50:51], v[110:111], v[50:51] op_sel_hi:[0,1]
	v_pk_fma_f32 v[62:63], v[8:9], v[80:81], v[100:101]
	v_pk_fma_f32 v[76:77], v[78:79], v[78:79], v[76:77]
	v_pk_mul_f32 v[80:81], v[48:49], v[48:49]
	v_pk_mul_f32 v[82:83], v[110:111], v[82:83] op_sel_hi:[0,1]
	v_pk_fma_f32 v[50:51], v[10:11], v[50:51], v[66:67]
	v_pk_fma_f32 v[80:81], v[62:63], v[62:63], v[80:81]
	v_add_f32_e32 v76, v76, v77
	v_pk_fma_f32 v[64:65], v[12:13], v[82:83], v[94:95]
	v_pk_mul_f32 v[82:83], v[50:51], v[50:51]
	v_add_f32_e32 v76, v80, v76
	v_pk_fma_f32 v[82:83], v[64:65], v[64:65], v[82:83]
	v_add_f32_e32 v76, v81, v76
	v_add_f32_e32 v76, v82, v76
	s_nop 2
	v_bfe_u32 v82, v46, 16, 1
	v_pk_mul_f32 v[52:53], v[110:111], v[52:53] op_sel_hi:[0,1]
	v_add3_u32 v46, v46, v82, s16
	s_nop 2
	v_bfe_u32 v77, v78, 16, 1
	s_nop 2
	v_pk_mul_f32 v[84:85], v[110:111], v[84:85] op_sel_hi:[0,1]
	v_pk_fma_f32 v[52:53], v[14:15], v[52:53], v[68:69]
	s_nop 2
	v_add3_u32 v77, v78, v77, s16
	v_lshlrev_b32_e32 v103, 16, v71
	v_lshlrev_b32_e32 v102, 16, v70
	v_and_b32_e32 v71, 0xffff0000, v71
	v_and_b32_e32 v70, 0xffff0000, v70
	v_pk_fma_f32 v[66:67], v[16:17], v[84:85], v[98:99]
	v_pk_mul_f32 v[54:55], v[110:111], v[54:55] op_sel_hi:[0,1]
	v_pk_mul_f32 v[84:85], v[52:53], v[52:53]
	v_lshrrev_b32_e32 v77, 16, v77
	s_nop 2
	v_pk_mul_f32 v[68:69], v[110:111], v[86:87] op_sel_hi:[0,1]
	v_pk_fma_f32 v[54:55], v[18:19], v[54:55], v[70:71]
	v_pk_fma_f32 v[84:85], v[66:67], v[66:67], v[84:85]
	v_add_f32_e32 v76, v83, v76
	v_cvt_pk_bf16_f32 v49, v63, v49
	v_cvt_pk_bf16_f32 v48, v62, v48
	v_cvt_pk_bf16_f32 v47, v79, v47
	v_and_or_b32 v46, v46, s12, v77
	v_lshlrev_b32_e32 v105, 16, v73
	v_lshlrev_b32_e32 v104, 16, v72
	v_and_b32_e32 v73, 0xffff0000, v73
	v_and_b32_e32 v72, 0xffff0000, v72
	v_pk_fma_f32 v[68:69], v[20:21], v[68:69], v[102:103]
	v_pk_mul_f32 v[56:57], v[110:111], v[56:57] op_sel_hi:[0,1]
	v_pk_mul_f32 v[86:87], v[54:55], v[54:55]
	v_add_f32_e32 v76, v84, v76
	global_store_dwordx4 v[34:35], v[46:49], off
	v_pk_mul_f32 v[70:71], v[110:111], v[88:89] op_sel_hi:[0,1]
	v_pk_fma_f32 v[56:57], v[22:23], v[56:57], v[72:73]
	s_nop 3
	v_pk_fma_f32 v[86:87], v[68:69], v[68:69], v[86:87]
	v_add_f32_e32 v76, v85, v76
	s_nop 7
	v_lshlrev_b32_e32 v107, 16, v75
	v_lshlrev_b32_e32 v106, 16, v74
	v_and_b32_e32 v75, 0xffff0000, v75
	v_and_b32_e32 v74, 0xffff0000, v74
	v_pk_fma_f32 v[70:71], v[24:25], v[70:71], v[104:105]
	v_pk_mul_f32 v[58:59], v[110:111], v[58:59] op_sel_hi:[0,1]
	v_pk_mul_f32 v[88:89], v[56:57], v[56:57]
	v_add_f32_e32 v76, v86, v76
	s_nop 3
	v_pk_mul_f32 v[72:73], v[110:111], v[90:91] op_sel_hi:[0,1]
	v_pk_fma_f32 v[58:59], v[26:27], v[58:59], v[74:75]
	v_pk_fma_f32 v[88:89], v[70:71], v[70:71], v[88:89]
	v_add_f32_e32 v76, v87, v76
	s_nop 3
	v_pk_fma_f32 v[72:73], v[28:29], v[72:73], v[106:107]
	v_pk_mul_f32 v[90:91], v[58:59], v[58:59]
	v_add_f32_e32 v76, v88, v76
	v_cvt_pk_bf16_f32 v49, v67, v53
	v_cvt_pk_bf16_f32 v48, v66, v52
	v_cvt_pk_bf16_f32 v47, v65, v51
	v_cvt_pk_bf16_f32 v46, v64, v50
	v_pk_mul_f32 v[74:75], v[110:111], v[92:93] op_sel_hi:[0,1]
	v_pk_fma_f32 v[90:91], v[72:73], v[72:73], v[90:91]
	v_add_f32_e32 v76, v89, v76
	global_store_dwordx4 v[34:35], v[46:49], off offset:1024
	v_pk_fma_f32 v[74:75], v[32:33], v[74:75], v[108:109]
	v_pk_mul_f32 v[92:93], v[60:61], v[60:61]
	s_nop 1
	v_add_f32_e32 v76, v90, v76
	s_nop 5
	v_pk_fma_f32 v[92:93], v[74:75], v[74:75], v[92:93]
	v_add_f32_e32 v76, v91, v76
	s_nop 5
	v_add_f32_e32 v76, v92, v76
	s_nop 5
	v_add_f32_e32 v76, v93, v76
	v_cvt_pk_bf16_f32 v49, v71, v57
	v_cvt_pk_bf16_f32 v48, v70, v56
	v_cvt_pk_bf16_f32 v47, v69, v55
	v_cvt_pk_bf16_f32 v46, v68, v54
	global_store_dwordx4 v[34:35], v[46:49], off offset:2048
	s_nop 3
	s_waitcnt lgkmcnt(0)
	s_nop 1
	v_add_f32_dpp v47, v76, v76 quad_perm:[1,0,3,2] row_mask:0xf bank_mask:0xf
	s_nop 3
	s_waitcnt lgkmcnt(0)
	s_nop 1
	v_add_f32_dpp v47, v47, v47 quad_perm:[2,3,0,1] row_mask:0xf bank_mask:0xf
	s_nop 1
	v_cvt_pk_bf16_f32 v51, v75, v61
	s_nop 0
	s_waitcnt lgkmcnt(0)
	s_nop 1
	v_add_f32_dpp v47, v47, v47 row_half_mirror row_mask:0xf bank_mask:0xf
	s_nop 3
	s_waitcnt lgkmcnt(0)
	s_nop 1
	v_add_f32_dpp v47, v47, v47 row_mirror row_mask:0xf bank_mask:0xf
	s_nop 3
	s_waitcnt lgkmcnt(0)
	v_mov_b32_e32 v50, v47
	v_mov_b32_e32 v46, v47
	s_nop 1
	v_permlane16_swap_b32_e32 v46, v50
	v_add_f32_e32 v46, v46, v50
	ds_bpermute_b32 v47, v45, v46
	s_nop 0
	v_cvt_pk_bf16_f32 v50, v74, v60
	v_cvt_pk_bf16_f32 v49, v73, v59
	v_cvt_pk_bf16_f32 v48, v72, v58
	global_store_dwordx4 v[34:35], v[48:51], off offset:3072
	s_and_saveexec_b64 s[10:11], s[0:1]
	s_cbranch_execz .LBB0_3811
	s_waitcnt lgkmcnt(0)
	v_add_f32_e32 v34, v46, v47
	v_fmamk_f32 v34, v34, 0x3a000000, v3
	v_mul_f32_e32 v35, 0x4b800000, v34
	v_cmp_gt_f32_e32 vcc, s15, v34
	v_readlane_b32 s18, v253, 0
	v_readlane_b32 s19, v253, 1
	v_cndmask_b32_e32 v34, v34, v35, vcc
	v_rsq_f32_e32 v34, v34
	s_add_u32 s18, s18, s13
	s_addc_u32 s19, s19, s14
	v_mul_f32_e32 v35, 0x45800000, v34
	v_cndmask_b32_e32 v34, v34, v35, vcc
	global_store_dword v251, v34, s[18:19]
	s_branch .LBB0_3811

; __device__ __forceinline__ float wave_sum(float v) {
; #pragma unroll
;     for (int o = 1; o < 64; o <<= 1) v += __shfl_xor(v, o);
;     return v;
; __device__ __forceinline__ void postnorm(const Ctx& c, const bf16* MF, bf16* XB, float* RS, const float* gpost, float* OUT) {
;     ...
;         const v4u* mr = (const v4u*)(MF + (size_t)row * DM) + c.lane; v4u* xr = (v4u*)(XB + (size_t)row * DM) + c.lane;
;         v4u mv[4], xv[4]; float v[4][8]; float s = 0.f;
; #pragma unroll
;         for (int j = 0; j < 4; ++j) { mv[j] = mr[64 * j]; xv[j] = xr[64 * j]; }
; #pragma unroll
;         for (int j = 0; j < 4; ++j)
; #pragma unroll
;             for (int k = 0; k < 4; ++k) { v[j][2 * k] = bflo(mv[j][k]); v[j][2 * k + 1] = bfhi(mv[j][k]); s += v[j][2 * k] * v[j][2 * k] + v[j][2 * k + 1] * v[j][2 * k + 1]; }
;         const float rs = rsqrtf(wave_sum(s) * (1.f / DM) + EPS);
.LBB0_4571:
	v_readlane_b32 s8, v253, 0
	v_readlane_b32 s9, v253, 1
	s_nop 1
	v_lshl_add_u64 v[34:35], s[8:9], 0, v[36:37]
	v_add_co_u32_e32 v58, vcc, 0xd400000, v34
	s_nop 1
	v_addc_co_u32_e32 v59, vcc, 0, v35, vcc
	s_waitcnt lgkmcnt(0)
	global_load_dwordx4 v[46:49], v[58:59], off
	global_load_dwordx4 v[50:53], v[58:59], off offset:1024
	global_load_dwordx4 v[54:57], v[58:59], off offset:2048
	s_nop 0
	global_load_dwordx4 v[58:61], v[58:59], off offset:3072
	v_add_co_u32_e32 v34, vcc, 0x9400000, v34
	s_waitcnt vmcnt(3)
	v_lshlrev_b32_e32 v79, 16, v47
	v_addc_co_u32_e32 v35, vcc, 0, v35, vcc
	global_load_dwordx4 v[62:65], v[34:35], off
	global_load_dwordx4 v[66:69], v[34:35], off offset:1024
	global_load_dwordx4 v[70:73], v[34:35], off offset:2048
	global_load_dwordx4 v[74:77], v[34:35], off offset:3072
	v_lshlrev_b32_e32 v78, 16, v46
	v_and_b32_e32 v47, 0xffff0000, v47
	v_and_b32_e32 v46, 0xffff0000, v46
	v_lshlrev_b32_e32 v81, 16, v49
	v_lshlrev_b32_e32 v80, 16, v48
	v_and_b32_e32 v49, 0xffff0000, v49
	v_and_b32_e32 v48, 0xffff0000, v48
	v_pk_mul_f32 v[94:95], v[46:47], v[46:47]
	v_pk_mul_f32 v[98:99], v[48:49], v[48:49]
	v_pk_fma_f32 v[94:95], v[78:79], v[78:79], v[94:95]
	s_waitcnt vmcnt(6)
	v_lshlrev_b32_e32 v83, 16, v51
	v_lshlrev_b32_e32 v82, 16, v50
	v_and_b32_e32 v51, 0xffff0000, v51
	v_and_b32_e32 v50, 0xffff0000, v50
	v_pk_fma_f32 v[98:99], v[80:81], v[80:81], v[98:99]
	v_add_f32_e32 v94, v94, v95
	v_pk_mul_f32 v[102:103], v[50:51], v[50:51]
	v_add_f32_e32 v94, v98, v94
	v_lshlrev_b32_e32 v85, 16, v53
	v_lshlrev_b32_e32 v84, 16, v52
	v_and_b32_e32 v53, 0xffff0000, v53
	v_and_b32_e32 v52, 0xffff0000, v52
	v_pk_fma_f32 v[102:103], v[82:83], v[82:83], v[102:103]
	v_add_f32_e32 v94, v99, v94
	v_pk_mul_f32 v[104:105], v[52:53], v[52:53]
	v_add_f32_e32 v94, v102, v94
	s_waitcnt vmcnt(5)
	v_lshlrev_b32_e32 v87, 16, v55
	v_lshlrev_b32_e32 v86, 16, v54
	v_and_b32_e32 v55, 0xffff0000, v55
	v_and_b32_e32 v54, 0xffff0000, v54
	v_pk_fma_f32 v[104:105], v[84:85], v[84:85], v[104:105]
	v_add_f32_e32 v94, v103, v94
	v_pk_mul_f32 v[106:107], v[54:55], v[54:55]
	v_add_f32_e32 v94, v104, v94
	v_lshlrev_b32_e32 v89, 16, v57
	v_lshlrev_b32_e32 v88, 16, v56
	v_and_b32_e32 v57, 0xffff0000, v57
	v_and_b32_e32 v56, 0xffff0000, v56
	v_pk_fma_f32 v[106:107], v[86:87], v[86:87], v[106:107]
	v_add_f32_e32 v94, v105, v94
	v_pk_mul_f32 v[108:109], v[56:57], v[56:57]
	v_add_f32_e32 v94, v106, v94
	s_waitcnt vmcnt(4)
	v_lshlrev_b32_e32 v91, 16, v59
	v_lshlrev_b32_e32 v90, 16, v58
	v_and_b32_e32 v59, 0xffff0000, v59
	v_and_b32_e32 v58, 0xffff0000, v58
	v_pk_fma_f32 v[108:109], v[88:89], v[88:89], v[108:109]
	v_add_f32_e32 v94, v107, v94
	v_pk_mul_f32 v[110:111], v[58:59], v[58:59]
	v_add_f32_e32 v94, v108, v94
	v_lshlrev_b32_e32 v93, 16, v61
	v_lshlrev_b32_e32 v92, 16, v60
	v_and_b32_e32 v61, 0xffff0000, v61
	v_and_b32_e32 v60, 0xffff0000, v60
	v_pk_fma_f32 v[110:111], v[90:91], v[90:91], v[110:111]
	v_add_f32_e32 v94, v109, v94
	v_pk_mul_f32 v[112:113], v[60:61], v[60:61]
	v_add_f32_e32 v94, v110, v94
	v_pk_fma_f32 v[112:113], v[92:93], v[92:93], v[112:113]
	v_add_f32_e32 v94, v111, v94
	v_add_f32_e32 v94, v112, v94
	v_add_f32_e32 v94, v113, v94
	s_waitcnt lgkmcnt(0)
	s_nop 1
	v_add_f32_dpp v98, v94, v94 quad_perm:[1,0,3,2] row_mask:0xf bank_mask:0xf
	s_waitcnt lgkmcnt(0)
	s_nop 1
	v_add_f32_dpp v102, v98, v98 quad_perm:[2,3,0,1] row_mask:0xf bank_mask:0xf
	s_waitcnt vmcnt(3)
	v_lshlrev_b32_e32 v97, 16, v63
	v_lshlrev_b32_e32 v96, 16, v62
	v_and_b32_e32 v63, 0xffff0000, v63
	s_waitcnt lgkmcnt(0)
	s_nop 1
	v_add_f32_dpp v104, v102, v102 row_half_mirror row_mask:0xf bank_mask:0xf
	v_and_b32_e32 v62, 0xffff0000, v62
	v_lshlrev_b32_e32 v101, 16, v65
	v_lshlrev_b32_e32 v100, 16, v64
	v_and_b32_e32 v65, 0xffff0000, v65
	s_waitcnt lgkmcnt(0)
	s_nop 1
	v_add_f32_dpp v106, v104, v104 row_mirror row_mask:0xf bank_mask:0xf
	v_and_b32_e32 v64, 0xffff0000, v64
	s_waitcnt vmcnt(0)
	v_lshlrev_b32_e32 v109, 16, v77
	v_and_b32_e32 v77, 0xffff0000, v77
	v_lshlrev_b32_e32 v95, 16, v67
	s_waitcnt lgkmcnt(0)
	v_mov_b32_e32 v108, v106
	s_nop 1
	v_permlane16_swap_b32_e32 v108, v106
	v_add_f32_e32 v108, v108, v106
	v_lshlrev_b32_e32 v94, 16, v66
	v_and_b32_e32 v67, 0xffff0000, v67
	v_and_b32_e32 v66, 0xffff0000, v66
	v_lshlrev_b32_e32 v99, 16, v69
	s_waitcnt lgkmcnt(0)
; __device__ __forceinline__ unsigned pk2(float lo, float hi) { return f2bf(lo) | (f2bf(hi) << 16); }
; __device__ __forceinline__ void postnorm(const Ctx& c, const bf16* MF, bf16* XB, float* RS, const float* gpost, float* OUT) {
;     ...
;         const float rs = rsqrtf(wave_sum(s) * (1.f / DM) + EPS);
;         float s2 = 0.f;
; #pragma unroll
;         for (int j = 0; j < 4; ++j) { const float* gp = gpost + (c.lane + 64 * j) * 8; const f32x4 g0 = *(CF4)gp, g1 = *(CF4)(gp + 4);
; #pragma unroll
;             for (int k = 0; k < 4; ++k) { const float ga = (k < 2) ? g0[2 * k] : g1[2 * k - 4], gb = (k < 2) ? g0[2 * k + 1] : g1[2 * k - 3];
;                 v[j][2 * k] = bflo(xv[j][k]) + v[j][2 * k] * rs * ga; v[j][2 * k + 1] = bfhi(xv[j][k]) + v[j][2 * k + 1] * rs * gb;
;                 s2 += v[j][2 * k] * v[j][2 * k] + v[j][2 * k + 1] * v[j][2 * k + 1]; } }
;         if (OUT) {
; #pragma unroll
;             for (int j = 0; j < 4; ++j) { float* op = OUT + (size_t)row * DM + (c.lane + 64 * j) * 8; *(f32x4*)op = (f32x4){v[j][0], v[j][1], v[j][2], v[j][3]}; *(f32x4*)(op + 4) = (f32x4){v[j][4], v[j][5], v[j][6], v[j][7]}; }
;         } else {
; #pragma unroll
;             for (int j = 0; j < 4; ++j) { v4u o; o.x = pk2(v[j][0], v[j][1]); o.y = pk2(v[j][2], v[j][3]); o.z = pk2(v[j][4], v[j][5]); o.w = pk2(v[j][6], v[j][7]); xr[64 * j] = o; }
;             const float rs2 = rsqrtf(wave_sum(s2) * (1.f / DM) + EPS); if (c.lane == 0) RS[row] = rs2;
	v_mov_b32_e32 v110, v108
	s_nop 1
	v_permlane32_swap_b32_e32 v108, v110
	v_add_f32_e32 v108, v108, v110
	v_fmamk_f32 v108, v108, 0x3a000000, v3
	v_mul_f32_e32 v110, 0x4b800000, v108
	v_cmp_gt_f32_e32 vcc, s13, v108
	v_lshlrev_b32_e32 v98, 16, v68
	v_and_b32_e32 v69, 0xffff0000, v69
	v_cndmask_b32_e32 v108, v108, v110, vcc
	v_rsq_f32_e32 v110, v108
	v_lshlrev_b32_e32 v108, 16, v76
	v_and_b32_e32 v76, 0xffff0000, v76
	v_and_b32_e32 v68, 0xffff0000, v68
	v_mul_f32_e32 v111, 0x45800000, v110
	v_cndmask_b32_e32 v110, v110, v111, vcc
	v_pk_mul_f32 v[46:47], v[110:111], v[46:47] op_sel_hi:[0,1]
	v_pk_mul_f32 v[78:79], v[110:111], v[78:79] op_sel_hi:[0,1]
	v_pk_mul_f32 v[48:49], v[110:111], v[48:49] op_sel_hi:[0,1]
	v_pk_fma_f32 v[46:47], v[38:39], v[46:47], v[62:63]
	v_pk_mul_f32 v[60:61], v[110:111], v[60:61] op_sel_hi:[0,1]
	v_pk_mul_f32 v[80:81], v[110:111], v[80:81] op_sel_hi:[0,1]
	v_pk_fma_f32 v[78:79], v[4:5], v[78:79], v[96:97]
	v_pk_fma_f32 v[48:49], v[6:7], v[48:49], v[64:65]
	v_pk_fma_f32 v[60:61], v[30:31], v[60:61], v[76:77]
	v_pk_mul_f32 v[76:77], v[46:47], v[46:47]
	v_pk_mul_f32 v[50:51], v[110:111], v[50:51] op_sel_hi:[0,1]
	v_pk_fma_f32 v[62:63], v[8:9], v[80:81], v[100:101]
	v_pk_fma_f32 v[76:77], v[78:79], v[78:79], v[76:77]
	v_pk_mul_f32 v[80:81], v[48:49], v[48:49]
	v_pk_mul_f32 v[82:83], v[110:111], v[82:83] op_sel_hi:[0,1]
	v_pk_fma_f32 v[50:51], v[10:11], v[50:51], v[66:67]
	v_pk_fma_f32 v[80:81], v[62:63], v[62:63], v[80:81]
	v_add_f32_e32 v76, v76, v77
	v_pk_fma_f32 v[64:65], v[12:13], v[82:83], v[94:95]
	v_pk_mul_f32 v[82:83], v[50:51], v[50:51]
	v_add_f32_e32 v76, v80, v76
	v_pk_fma_f32 v[82:83], v[64:65], v[64:65], v[82:83]
	v_add_f32_e32 v76, v81, v76
	v_add_f32_e32 v76, v82, v76
	s_nop 2
	v_bfe_u32 v82, v46, 16, 1
	v_pk_mul_f32 v[52:53], v[110:111], v[52:53] op_sel_hi:[0,1]
	v_add3_u32 v46, v46, v82, s14
	s_nop 2
	v_bfe_u32 v77, v78, 16, 1
	s_nop 2
	v_pk_mul_f32 v[84:85], v[110:111], v[84:85] op_sel_hi:[0,1]
	v_pk_fma_f32 v[52:53], v[14:15], v[52:53], v[68:69]
	s_nop 2
	v_add3_u32 v77, v78, v77, s14
	v_lshlrev_b32_e32 v103, 16, v71
	v_lshlrev_b32_e32 v102, 16, v70
	v_and_b32_e32 v71, 0xffff0000, v71
	v_and_b32_e32 v70, 0xffff0000, v70
	v_pk_fma_f32 v[66:67], v[16:17], v[84:85], v[98:99]
	v_pk_mul_f32 v[54:55], v[110:111], v[54:55] op_sel_hi:[0,1]
	v_pk_mul_f32 v[84:85], v[52:53], v[52:53]
	v_lshrrev_b32_e32 v77, 16, v77
	s_nop 2
	v_pk_mul_f32 v[68:69], v[110:111], v[86:87] op_sel_hi:[0,1]
	v_pk_fma_f32 v[54:55], v[18:19], v[54:55], v[70:71]
	v_pk_fma_f32 v[84:85], v[66:67], v[66:67], v[84:85]
	v_add_f32_e32 v76, v83, v76
	v_cvt_pk_bf16_f32 v49, v63, v49
	v_cvt_pk_bf16_f32 v48, v62, v48
	v_cvt_pk_bf16_f32 v47, v79, v47
	v_and_or_b32 v46, v46, s10, v77
	v_lshlrev_b32_e32 v105, 16, v73
	v_lshlrev_b32_e32 v104, 16, v72
	v_and_b32_e32 v73, 0xffff0000, v73
	v_and_b32_e32 v72, 0xffff0000, v72
	v_pk_fma_f32 v[68:69], v[20:21], v[68:69], v[102:103]
	v_pk_mul_f32 v[56:57], v[110:111], v[56:57] op_sel_hi:[0,1]
	v_pk_mul_f32 v[86:87], v[54:55], v[54:55]
	v_add_f32_e32 v76, v84, v76
	global_store_dwordx4 v[34:35], v[46:49], off
	v_pk_mul_f32 v[70:71], v[110:111], v[88:89] op_sel_hi:[0,1]
	v_pk_fma_f32 v[56:57], v[22:23], v[56:57], v[72:73]
	s_nop 3
	v_pk_fma_f32 v[86:87], v[68:69], v[68:69], v[86:87]
	v_add_f32_e32 v76, v85, v76
	s_nop 7
	v_lshlrev_b32_e32 v107, 16, v75
	v_lshlrev_b32_e32 v106, 16, v74
	v_and_b32_e32 v75, 0xffff0000, v75
	v_and_b32_e32 v74, 0xffff0000, v74
	v_pk_fma_f32 v[70:71], v[24:25], v[70:71], v[104:105]
	v_pk_mul_f32 v[58:59], v[110:111], v[58:59] op_sel_hi:[0,1]
	v_pk_mul_f32 v[88:89], v[56:57], v[56:57]
	v_add_f32_e32 v76, v86, v76
	s_nop 3
	v_pk_mul_f32 v[72:73], v[110:111], v[90:91] op_sel_hi:[0,1]
	v_pk_fma_f32 v[58:59], v[26:27], v[58:59], v[74:75]
	v_pk_fma_f32 v[88:89], v[70:71], v[70:71], v[88:89]
	v_add_f32_e32 v76, v87, v76
	s_nop 3
	v_pk_fma_f32 v[72:73], v[28:29], v[72:73], v[106:107]
	v_pk_mul_f32 v[90:91], v[58:59], v[58:59]
	v_add_f32_e32 v76, v88, v76
	v_cvt_pk_bf16_f32 v49, v67, v53
	v_cvt_pk_bf16_f32 v48, v66, v52
	v_cvt_pk_bf16_f32 v47, v65, v51
	v_cvt_pk_bf16_f32 v46, v64, v50
	v_pk_mul_f32 v[74:75], v[110:111], v[92:93] op_sel_hi:[0,1]
	v_pk_fma_f32 v[90:91], v[72:73], v[72:73], v[90:91]
	v_add_f32_e32 v76, v89, v76
	global_store_dwordx4 v[34:35], v[46:49], off offset:1024
	v_pk_fma_f32 v[74:75], v[32:33], v[74:75], v[108:109]
	v_pk_mul_f32 v[92:93], v[60:61], v[60:61]
	s_nop 1
	v_add_f32_e32 v76, v90, v76
	s_nop 5
	v_pk_fma_f32 v[92:93], v[74:75], v[74:75], v[92:93]
	v_add_f32_e32 v76, v91, v76
	s_nop 5
	v_add_f32_e32 v76, v92, v76
	s_nop 5
	v_add_f32_e32 v76, v93, v76
	v_cvt_pk_bf16_f32 v49, v71, v57
	v_cvt_pk_bf16_f32 v48, v70, v56
	v_cvt_pk_bf16_f32 v47, v69, v55
	v_cvt_pk_bf16_f32 v46, v68, v54
	global_store_dwordx4 v[34:35], v[46:49], off offset:2048
	s_nop 3
	s_waitcnt lgkmcnt(0)
	s_nop 1
	v_add_f32_dpp v47, v76, v76 quad_perm:[1,0,3,2] row_mask:0xf bank_mask:0xf
	s_nop 3
	s_waitcnt lgkmcnt(0)
	s_nop 1
	v_add_f32_dpp v47, v47, v47 quad_perm:[2,3,0,1] row_mask:0xf bank_mask:0xf
	s_nop 1
	v_cvt_pk_bf16_f32 v51, v75, v61
	s_nop 0
	s_waitcnt lgkmcnt(0)
	s_nop 1
	v_add_f32_dpp v47, v47, v47 row_half_mirror row_mask:0xf bank_mask:0xf
	s_nop 3
	s_waitcnt lgkmcnt(0)
	s_nop 1
	v_add_f32_dpp v47, v47, v47 row_mirror row_mask:0xf bank_mask:0xf
	s_nop 3
	s_waitcnt lgkmcnt(0)
	v_mov_b32_e32 v50, v47
	v_mov_b32_e32 v46, v47
	s_nop 1
	v_permlane16_swap_b32_e32 v46, v50
	v_add_f32_e32 v46, v46, v50
	ds_bpermute_b32 v47, v45, v46
	s_nop 0
	v_cvt_pk_bf16_f32 v50, v74, v60
	v_cvt_pk_bf16_f32 v49, v73, v59
	v_cvt_pk_bf16_f32 v48, v72, v58
	global_store_dwordx4 v[34:35], v[48:51], off offset:3072
	s_and_saveexec_b64 s[8:9], s[0:1]
	s_cbranch_execz .LBB0_4570
	s_waitcnt lgkmcnt(0)
	v_add_f32_e32 v34, v46, v47
	v_fmamk_f32 v34, v34, 0x3a000000, v3
	v_mul_f32_e32 v35, 0x4b800000, v34
	v_cmp_gt_f32_e32 vcc, s13, v34
	v_readlane_b32 s16, v253, 0
	v_readlane_b32 s17, v253, 1
	v_cndmask_b32_e32 v34, v34, v35, vcc
	v_rsq_f32_e32 v34, v34
	s_add_u32 s16, s16, s11
	s_addc_u32 s17, s17, s12
	v_mul_f32_e32 v35, 0x45800000, v34
	v_cndmask_b32_e32 v34, v34, v35, vcc
	global_store_dword v251, v34, s[16:17]
	s_branch .LBB0_4570
